# half-tile round: dropped unused B1 fragment reads and dead bj=1 epilogue VALU in the half unit
# speedup vs baseline: 1.0074x; 1.0074x over previous
; #define PG8_STAGE(bufoff, gbase, voff) do { _Pragma("unroll") for (int _i = 0; _i < 2; ++_i) \
;         __builtin_amdgcn_global_load_lds((const unsigned*)((const char*)(gbase) + (voff)[_i]), (PG8_LAS unsigned*)(lds + (bufoff) + ldsw + _i * 8192), 16, 0, 0); } while (0)
; #define PG8_LDA(dst, b, h) do { _Pragma("unroll") for (int m = 0; m < 4; ++m) _Pragma("unroll") for (int k = 0; k < 2; ++k) dst[m][k] = *(const PG8_LAS bf16x8*)(lds + PG8_SA(b, h) + aoff + m * 2048 + k * 1024); } while (0)
; #define PG8_LDB(dst, b, h) do { _Pragma("unroll") for (int n = 0; n < 2; ++n) _Pragma("unroll") for (int k = 0; k < 2; ++k) dst[n][k] = *(const PG8_LAS bf16x8*)(lds + PG8_SB(b, h) + boff + n * 2048 + k * 1024); } while (0)
; #define PG8_WAIT_V(n) asm volatile("s_waitcnt vmcnt(" #n ")" ::: "memory")
; #define PG8_WAIT_L(n) asm volatile("s_waitcnt lgkmcnt(" #n ")" ::: "memory")
; #define PG8_BAR __builtin_amdgcn_s_barrier()
; #define PG8_SCHED __builtin_amdgcn_sched_barrier(0)
; template <class Epi, class Sched, bool STAMP = false>
; __device__ __forceinline__ void gemm_phase(PG8_LAS unsigned char* lds, const Gemm g, const Sched& S, const Epi& E, unsigned long long* stamps) {
;     ...
;         for (int t = 0; t < nt; t += 2) {
;             const bool last = (t == nt - 2);
;             const char* a1 = cA + (size_t)(t + 1) * kstep;
;             const char* a2 = last ? nA : cA + (size_t)(t + 2) * kstep; const char* b2 = last ? nB : cB + (size_t)(t + 2) * kstep;
;             const char* a3 = a2 + kstep; const char* b3 = b2 + kstep;
;             if (last && has_next) S.a_ready(nxt);
;             PG8_LDB(B0, 0, 0); PG8_SCHED; PG8_LDA(At, 0, 0); PG8_STAGE(PG8_SA(1, 1), a1 + hstep, voffA);
;             PG8_WAIT_L(8); PG8_BAR; PG8_WAIT_L(0); PG8_MMA(0, 0, At, B0); PG8_BAR; PG8_SCHED;
;             PG8_LDB(B1, 0, 1); PG8_STAGE(PG8_SB(0, 0), b2, voffB);
;             PG8_BAR; PG8_WAIT_L(0); PG8_MMA(0, 1, At, B1); PG8_BAR;
;             PG8_LDA(At, 0, 1); PG8_STAGE(PG8_SA(0, 0), a2, voffA);
;             PG8_BAR; PG8_WAIT_L(0); PG8_MMA(1, 0, At, B0); PG8_BAR; PG8_SCHED;
;             PG8_STAGE(PG8_SB(0, 1), b2 + hstep, voffB);
;             PG8_WAIT_V(6); PG8_BAR; PG8_MMA(1, 1, At, B1); PG8_BAR;
;             PG8_LDB(B0, 1, 0); PG8_SCHED; PG8_LDA(At, 1, 0); PG8_STAGE(PG8_SA(0, 1), a2 + hstep, voffA);
.Lgu1_half_loop:
	ds_read_b128 v[140:143], v148
	ds_read_b128 v[166:169], v149
	ds_read_b128 v[170:173], v150
	ds_read_b128 v[174:177], v151
	s_add_u32 s16, s14, 0x100
	s_addc_u32 s17, s15, 0
	s_cmp_eq_u32 s77, 12
	s_cselect_b32 s29, s5, s17
	s_cselect_b32 s28, s4, s16
	s_cselect_b32 s19, s1, s76
	s_cselect_b32 s18, s0, s75
	s_mov_b32 m0, s68
	v_lshl_add_u64 v[210:211], s[14:15], 0, v[132:133]
	ds_read_b128 v[178:181], v146
	ds_read_b128 v[182:185], v146 offset:1024
	ds_read_b128 v[186:189], v146 offset:2048
	ds_read_b128 v[190:193], v146 offset:3072
	ds_read_b128 v[194:197], v146 offset:4096
	ds_read_b128 v[198:201], v146 offset:5120
	ds_read_b128 v[202:205], v146 offset:6144
	ds_read_b128 v[206:209], v146 offset:7168
	global_load_lds_dwordx4 v[210:211], off
	v_lshl_add_u64 v[210:211], s[14:15], 0, v[134:135]
	s_mov_b32 m0, s69
	s_nop 0
	global_load_lds_dwordx4 v[210:211], off
	s_waitcnt lgkmcnt(8)
	s_barrier
	s_waitcnt lgkmcnt(0)
	s_setprio 1
	s_waitcnt lgkmcnt(0)
	v_mfma_f32_16x16x32_bf16 v[124:127], v[140:143], v[178:181], v[124:127]
	v_mfma_f32_16x16x32_bf16 v[120:123], v[170:173], v[178:181], v[120:123]
	v_mfma_f32_16x16x32_bf16 v[108:111], v[140:143], v[186:189], v[108:111]
	v_mfma_f32_16x16x32_bf16 v[104:107], v[170:173], v[186:189], v[104:107]
	v_mfma_f32_16x16x32_bf16 v[92:95], v[140:143], v[194:197], v[92:95]
	v_mfma_f32_16x16x32_bf16 v[88:91], v[170:173], v[194:197], v[88:91]
	v_mfma_f32_16x16x32_bf16 v[76:79], v[140:143], v[202:205], v[76:79]
	v_mfma_f32_16x16x32_bf16 v[72:75], v[170:173], v[202:205], v[72:75]
	v_mfma_f32_16x16x32_bf16 v[124:127], v[166:169], v[182:185], v[124:127]
	v_mfma_f32_16x16x32_bf16 v[120:123], v[174:177], v[182:185], v[120:123]
	v_mfma_f32_16x16x32_bf16 v[108:111], v[166:169], v[190:193], v[108:111]
	v_mfma_f32_16x16x32_bf16 v[104:107], v[174:177], v[190:193], v[104:107]
	v_mfma_f32_16x16x32_bf16 v[92:95], v[166:169], v[198:201], v[92:95]
	v_mfma_f32_16x16x32_bf16 v[88:91], v[174:177], v[198:201], v[88:91]
	v_mfma_f32_16x16x32_bf16 v[76:79], v[166:169], v[206:209], v[76:79]
	v_mfma_f32_16x16x32_bf16 v[72:75], v[174:177], v[206:209], v[72:75]
	s_setprio 0
	s_barrier
	s_mov_b32 m0, s52
	v_lshl_add_u64 v[226:227], s[18:19], 0, v[130:131]
	global_load_lds_dwordx4 v[226:227], off
	v_lshl_add_u64 v[228:229], s[18:19], 0, v[128:129]
	s_mov_b32 m0, s53
	s_nop 0
	global_load_lds_dwordx4 v[228:229], off
	s_barrier
	s_waitcnt lgkmcnt(0)
	s_setprio 1
	s_waitcnt lgkmcnt(0)
	s_setprio 0
	s_mov_b32 m0, s33
	v_lshl_add_u64 v[230:231], s[28:29], 0, v[130:131]
	s_barrier
	ds_read_b128 v[178:181], v146 offset:16384
	ds_read_b128 v[182:185], v146 offset:17408
	ds_read_b128 v[186:189], v146 offset:18432
	ds_read_b128 v[190:193], v146 offset:19456
	ds_read_b128 v[194:197], v146 offset:20480
	ds_read_b128 v[198:201], v146 offset:21504
	ds_read_b128 v[202:205], v146 offset:22528
	ds_read_b128 v[206:209], v146 offset:23552
	global_load_lds_dwordx4 v[230:231], off
	v_lshl_add_u64 v[232:233], s[28:29], 0, v[128:129]
	s_mov_b32 m0, s54
	s_nop 0
	global_load_lds_dwordx4 v[232:233], off
	s_barrier
	s_waitcnt lgkmcnt(0)
	s_setprio 1
	s_waitcnt lgkmcnt(0)
	v_mfma_f32_16x16x32_bf16 v[60:63], v[140:143], v[178:181], v[60:63]
	v_mfma_f32_16x16x32_bf16 v[56:59], v[170:173], v[178:181], v[56:59]
	v_mfma_f32_16x16x32_bf16 v[44:47], v[140:143], v[186:189], v[44:47]
	v_mfma_f32_16x16x32_bf16 v[40:43], v[170:173], v[186:189], v[40:43]
	v_mfma_f32_16x16x32_bf16 v[28:31], v[140:143], v[194:197], v[28:31]
	v_mfma_f32_16x16x32_bf16 v[24:27], v[170:173], v[194:197], v[24:27]
	v_mfma_f32_16x16x32_bf16 v[12:15], v[140:143], v[202:205], v[12:15]
	v_mfma_f32_16x16x32_bf16 v[8:11], v[170:173], v[202:205], v[8:11]
	v_mfma_f32_16x16x32_bf16 v[60:63], v[166:169], v[182:185], v[60:63]
	v_mfma_f32_16x16x32_bf16 v[56:59], v[174:177], v[182:185], v[56:59]
	v_mfma_f32_16x16x32_bf16 v[44:47], v[166:169], v[190:193], v[44:47]
	v_mfma_f32_16x16x32_bf16 v[40:43], v[174:177], v[190:193], v[40:43]
	v_mfma_f32_16x16x32_bf16 v[28:31], v[166:169], v[198:201], v[28:31]
	v_mfma_f32_16x16x32_bf16 v[24:27], v[174:177], v[198:201], v[24:27]
	v_mfma_f32_16x16x32_bf16 v[12:15], v[166:169], v[206:209], v[12:15]
	v_mfma_f32_16x16x32_bf16 v[8:11], v[174:177], v[206:209], v[8:11]
	s_setprio 0
	s_barrier
	s_add_u32 s14, s18, 0x44000
	s_addc_u32 s15, s19, 0
	s_mov_b32 m0, s55
	v_lshl_add_u64 v[140:141], s[14:15], 0, v[130:131]
	global_load_lds_dwordx4 v[140:141], off
	v_lshl_add_u64 v[140:141], s[14:15], 0, v[128:129]
	s_mov_b32 m0, s56
	s_nop 0
	global_load_lds_dwordx4 v[140:141], off
	s_waitcnt vmcnt(6)
	s_barrier
	s_setprio 1
	s_setprio 0
	s_barrier
	ds_read_b128 v[140:143], v156
	ds_read_b128 v[166:169], v157
	ds_read_b128 v[170:173], v159
	ds_read_b128 v[174:177], v160
	s_add_u32 s14, s28, 0x44000
	s_addc_u32 s15, s29, 0
	s_mov_b32 m0, s57
	v_lshl_add_u64 v[210:211], s[14:15], 0, v[130:131]
	ds_read_b128 v[178:181], v146 offset:32768
	ds_read_b128 v[182:185], v146 offset:33792
	ds_read_b128 v[186:189], v146 offset:34816
	ds_read_b128 v[190:193], v146 offset:35840
	ds_read_b128 v[194:197], v146 offset:36864
	ds_read_b128 v[198:201], v146 offset:37888
	ds_read_b128 v[202:205], v146 offset:38912
	ds_read_b128 v[206:209], v146 offset:39936
	global_load_lds_dwordx4 v[210:211], off
	v_lshl_add_u64 v[210:211], s[14:15], 0, v[128:129]
	s_mov_b32 m0, s58
	s_nop 0
	global_load_lds_dwordx4 v[210:211], off
	s_waitcnt lgkmcnt(8)
	s_barrier
; DI float ex2(float x) { return __builtin_amdgcn_exp2f(x); }
; #define PG8_STAGE(bufoff, gbase, voff) do { _Pragma("unroll") for (int _i = 0; _i < 2; ++_i) \
;         __builtin_amdgcn_global_load_lds((const unsigned*)((const char*)(gbase) + (voff)[_i]), (PG8_LAS unsigned*)(lds + (bufoff) + ldsw + _i * 8192), 16, 0, 0); } while (0)
; #define PG8_LDA(dst, b, h) do { _Pragma("unroll") for (int m = 0; m < 4; ++m) _Pragma("unroll") for (int k = 0; k < 2; ++k) dst[m][k] = *(const PG8_LAS bf16x8*)(lds + PG8_SA(b, h) + aoff + m * 2048 + k * 1024); } while (0)
; #define PG8_WAIT_V(n) asm volatile("s_waitcnt vmcnt(" #n ")" ::: "memory")
; #define PG8_WAIT_L(n) asm volatile("s_waitcnt lgkmcnt(" #n ")" ::: "memory")
; #define PG8_BAR __builtin_amdgcn_s_barrier()
;     DI void operator()(const f32x4 (&acc)[2][2][4][2], const Unit& u, int wr, int wc, int fr, int fq) const {
;         const int row0 = u.pm * BM + wr * 64 + fr, hcol0 = ((u.pn * BM + wc * 32) >> 1) + 4 * fq;
; #pragma unroll
;         for (int ai = 0; ai < 2; ++ai)
; #pragma unroll
;             for (int m = 0; m < 4; ++m) { u16* rowp = O + (size_t)(row0 + ai * HALF + m * 16) * ldc + hcol0;
; #pragma unroll
;                 for (int bj = 0; bj < 2; ++bj) { const f32x4 g = acc[ai][bj][m][0], up = acc[ai][bj][m][1]; float r[4];
; #pragma unroll
;                     for (int j = 0; j < 4; ++j) r[j] = g[j] * up[j] * __builtin_amdgcn_rcpf(1.f + ex2(-LOG2E * g[j]));
;                     uint2 w = {pack2(r[0], r[1]), pack2(r[2], r[3])}; *(uint2*)(rowp + bj * (HALF / 2)) = w; } }
; template <class Epi, class Sched, bool STAMP = false>
; __device__ __forceinline__ void gemm_phase(PG8_LAS unsigned char* lds, const Gemm g, const Sched& S, const Epi& E, unsigned long long* stamps) {
;     ...
;             PG8_LDB(B0, 1, 0); PG8_SCHED; PG8_LDA(At, 1, 0); PG8_STAGE(PG8_SA(0, 1), a2 + hstep, voffA);
;             PG8_WAIT_L(8); PG8_BAR; PG8_WAIT_L(0); PG8_MMA(0, 0, At, B0); PG8_BAR; PG8_SCHED;
;             PG8_LDB(B1, 1, 1); PG8_STAGE(PG8_SB(1, 0), b3, voffB);
;             PG8_BAR; PG8_WAIT_L(0); PG8_MMA(0, 1, At, B1); PG8_BAR;
;             PG8_LDA(At, 1, 1); PG8_STAGE(PG8_SA(1, 0), a3, voffA);
;             PG8_BAR; PG8_WAIT_L(0); PG8_MMA(1, 0, At, B0); PG8_BAR; PG8_SCHED;
;             PG8_STAGE(PG8_SB(1, 1), b3 + hstep, voffB);
;             PG8_WAIT_V(6); PG8_BAR; PG8_MMA(1, 1, At, B1); PG8_BAR;
;         }
	s_waitcnt lgkmcnt(0)
	s_setprio 1
	s_waitcnt lgkmcnt(0)
	v_mfma_f32_16x16x32_bf16 v[124:127], v[140:143], v[178:181], v[124:127]
	v_mfma_f32_16x16x32_bf16 v[120:123], v[170:173], v[178:181], v[120:123]
	v_mfma_f32_16x16x32_bf16 v[108:111], v[140:143], v[186:189], v[108:111]
	v_mfma_f32_16x16x32_bf16 v[104:107], v[170:173], v[186:189], v[104:107]
	v_mfma_f32_16x16x32_bf16 v[92:95], v[140:143], v[194:197], v[92:95]
	v_mfma_f32_16x16x32_bf16 v[88:91], v[170:173], v[194:197], v[88:91]
	v_mfma_f32_16x16x32_bf16 v[76:79], v[140:143], v[202:205], v[76:79]
	v_mfma_f32_16x16x32_bf16 v[72:75], v[170:173], v[202:205], v[72:75]
	v_mfma_f32_16x16x32_bf16 v[124:127], v[166:169], v[182:185], v[124:127]
	v_mfma_f32_16x16x32_bf16 v[120:123], v[174:177], v[182:185], v[120:123]
	v_mfma_f32_16x16x32_bf16 v[108:111], v[166:169], v[190:193], v[108:111]
	v_mfma_f32_16x16x32_bf16 v[104:107], v[174:177], v[190:193], v[104:107]
	v_mfma_f32_16x16x32_bf16 v[92:95], v[166:169], v[198:201], v[92:95]
	v_mfma_f32_16x16x32_bf16 v[88:91], v[174:177], v[198:201], v[88:91]
	v_mfma_f32_16x16x32_bf16 v[76:79], v[166:169], v[206:209], v[76:79]
	v_mfma_f32_16x16x32_bf16 v[72:75], v[174:177], v[206:209], v[72:75]
	s_setprio 0
	s_barrier
	s_mov_b32 m0, s61
	v_lshl_add_u64 v[226:227], v[226:227], 0, s[6:7]
	global_load_lds_dwordx4 v[226:227], off
	v_lshl_add_u64 v[226:227], v[228:229], 0, s[6:7]
	s_mov_b32 m0, s62
	s_nop 0
	global_load_lds_dwordx4 v[226:227], off
	s_barrier
	s_waitcnt lgkmcnt(0)
	s_setprio 1
	s_waitcnt lgkmcnt(0)
	s_setprio 0
	s_mov_b32 m0, s63
	v_lshl_add_u64 v[226:227], v[230:231], 0, s[6:7]
	s_barrier
	ds_read_b128 v[178:181], v146 offset:49152
	ds_read_b128 v[182:185], v146 offset:50176
	ds_read_b128 v[186:189], v146 offset:51200
	ds_read_b128 v[190:193], v146 offset:52224
	ds_read_b128 v[194:197], v146 offset:53248
	ds_read_b128 v[198:201], v146 offset:54272
	ds_read_b128 v[202:205], v146 offset:55296
	ds_read_b128 v[206:209], v146 offset:56320
	global_load_lds_dwordx4 v[226:227], off
	v_lshl_add_u64 v[226:227], v[232:233], 0, s[6:7]
	s_mov_b32 m0, s64
	s_nop 0
	global_load_lds_dwordx4 v[226:227], off
	s_barrier
	s_waitcnt lgkmcnt(0)
	s_setprio 1
	s_waitcnt lgkmcnt(0)
	v_mfma_f32_16x16x32_bf16 v[60:63], v[140:143], v[178:181], v[60:63]
	v_mfma_f32_16x16x32_bf16 v[56:59], v[170:173], v[178:181], v[56:59]
	v_mfma_f32_16x16x32_bf16 v[44:47], v[140:143], v[186:189], v[44:47]
	v_mfma_f32_16x16x32_bf16 v[40:43], v[170:173], v[186:189], v[40:43]
	v_mfma_f32_16x16x32_bf16 v[28:31], v[140:143], v[194:197], v[28:31]
	v_mfma_f32_16x16x32_bf16 v[24:27], v[170:173], v[194:197], v[24:27]
	v_mfma_f32_16x16x32_bf16 v[12:15], v[140:143], v[202:205], v[12:15]
	v_mfma_f32_16x16x32_bf16 v[8:11], v[170:173], v[202:205], v[8:11]
	v_mfma_f32_16x16x32_bf16 v[60:63], v[166:169], v[182:185], v[60:63]
	v_mfma_f32_16x16x32_bf16 v[56:59], v[174:177], v[182:185], v[56:59]
	v_mfma_f32_16x16x32_bf16 v[44:47], v[166:169], v[190:193], v[44:47]
	v_mfma_f32_16x16x32_bf16 v[40:43], v[174:177], v[190:193], v[40:43]
	v_mfma_f32_16x16x32_bf16 v[28:31], v[166:169], v[198:201], v[28:31]
	v_mfma_f32_16x16x32_bf16 v[24:27], v[174:177], v[198:201], v[24:27]
	v_mfma_f32_16x16x32_bf16 v[12:15], v[166:169], v[206:209], v[12:15]
	v_mfma_f32_16x16x32_bf16 v[8:11], v[174:177], v[206:209], v[8:11]
	s_setprio 0
	s_barrier
	s_add_u32 s14, s18, 0x44080
	s_addc_u32 s15, s19, 0
	s_mov_b32 m0, s65
	v_lshl_add_u64 v[140:141], s[14:15], 0, v[130:131]
	global_load_lds_dwordx4 v[140:141], off
	v_lshl_add_u64 v[140:141], s[14:15], 0, v[128:129]
	s_mov_b32 m0, s66
	s_nop 0
	global_load_lds_dwordx4 v[140:141], off
	s_waitcnt vmcnt(6)
	s_barrier
	s_setprio 1
	s_setprio 0
	s_add_i32 s77, s77, 2
	s_add_u32 s75, s75, 0x100
	s_addc_u32 s76, s76, 0
	s_cmp_gt_u32 s77, 13
	s_mov_b64 s[14:15], s[16:17]
	s_barrier
	s_cbranch_scc0 .Lgu1_half_loop
	v_mul_f32_e32 v168, 0xbfb8aa3b, v124
	v_mul_f32_e32 v169, 0xbfb8aa3b, v125
	v_mul_f32_e32 v170, 0xbfb8aa3b, v126
	v_mul_f32_e32 v171, 0xbfb8aa3b, v127
	v_exp_f32_e32 v168, v168
	v_exp_f32_e32 v169, v169
	v_exp_f32_e32 v170, v170
	v_exp_f32_e32 v171, v171
	v_add_f32_e32 v168, 1.0, v168
	v_add_f32_e32 v169, 1.0, v169
	v_add_f32_e32 v170, 1.0, v170
	v_add_f32_e32 v171, 1.0, v171
	v_rcp_f32_e32 v168, v168
	v_rcp_f32_e32 v169, v169
	v_rcp_f32_e32 v170, v170
	v_rcp_f32_e32 v171, v171
	s_lshl_b32 s10, s74, 8
	v_pk_mul_f32 v[122:123], v[126:127], v[122:123]
	v_pk_mul_f32 v[120:121], v[124:125], v[120:121]
	s_or_b32 s10, s10, s60
	s_or_b32 s10, s10, s98
	v_pk_mul_f32 v[120:121], v[120:121], v[168:169]
	v_pk_mul_f32 v[122:123], v[122:123], v[170:171]
	s_ashr_i32 s10, s10, 1
	v_cvt_pk_bf16_f32 v120, v120, v121
	v_cvt_pk_bf16_f32 v121, v122, v123
	v_or_b32_e32 v140, s10, v147
	v_lshl_add_u32 v165, s73, 8, v145
	v_ashrrev_i32_e32 v141, 31, v140
	v_mov_b64_e32 v[142:143], s[12:13]
	v_mad_i64_i32 v[166:167], s[14:15], v165, s70, v[142:143]
	v_lshlrev_b64 v[140:141], 1, v[140:141]
	v_lshl_add_u64 v[166:167], v[166:167], 0, v[140:141]
	global_store_dwordx2 v[166:167], v[120:121], off
	v_mul_f32_e32 v116, 0xbfb8aa3b, v110
	v_mul_f32_e32 v114, 0xbfb8aa3b, v108
	v_mul_f32_e32 v115, 0xbfb8aa3b, v109
	v_mul_f32_e32 v117, 0xbfb8aa3b, v111
	v_exp_f32_e32 v114, v114
	v_exp_f32_e32 v115, v115
	v_exp_f32_e32 v116, v116
	v_exp_f32_e32 v117, v117
	v_add_f32_e32 v114, 1.0, v114
	v_add_f32_e32 v115, 1.0, v115
	v_add_f32_e32 v116, 1.0, v116
	v_add_f32_e32 v117, 1.0, v117
	v_rcp_f32_e32 v114, v114
	v_rcp_f32_e32 v115, v115
	v_rcp_f32_e32 v116, v116
	v_rcp_f32_e32 v117, v117
	v_pk_mul_f32 v[106:107], v[110:111], v[106:107]
	v_pk_mul_f32 v[104:105], v[108:109], v[104:105]
	v_pk_mul_f32 v[104:105], v[104:105], v[114:115]
; DI float ex2(float x) { return __builtin_amdgcn_exp2f(x); }
;     DI void operator()(const f32x4 (&acc)[2][2][4][2], const Unit& u, int wr, int wc, int fr, int fq) const {
;         const int row0 = u.pm * BM + wr * 64 + fr, hcol0 = ((u.pn * BM + wc * 32) >> 1) + 4 * fq;
; #pragma unroll
;         for (int ai = 0; ai < 2; ++ai)
; #pragma unroll
;             for (int m = 0; m < 4; ++m) { u16* rowp = O + (size_t)(row0 + ai * HALF + m * 16) * ldc + hcol0;
; #pragma unroll
;                 for (int bj = 0; bj < 2; ++bj) { const f32x4 g = acc[ai][bj][m][0], up = acc[ai][bj][m][1]; float r[4];
; #pragma unroll
;                     for (int j = 0; j < 4; ++j) r[j] = g[j] * up[j] * __builtin_amdgcn_rcpf(1.f + ex2(-LOG2E * g[j]));
;                     uint2 w = {pack2(r[0], r[1]), pack2(r[2], r[3])}; *(uint2*)(rowp + bj * (HALF / 2)) = w; } }
	v_pk_mul_f32 v[106:107], v[106:107], v[116:117]
	v_cvt_pk_bf16_f32 v104, v104, v105
	v_cvt_pk_bf16_f32 v105, v106, v107
	v_or_b32_e32 v112, 16, v165
	v_mad_i64_i32 v[112:113], s[14:15], v112, s70, v[142:143]
	v_lshl_add_u64 v[112:113], v[112:113], 0, v[140:141]
	global_store_dwordx2 v[112:113], v[104:105], off
	v_mul_f32_e32 v100, 0xbfb8aa3b, v94
	v_mul_f32_e32 v98, 0xbfb8aa3b, v92
	v_mul_f32_e32 v99, 0xbfb8aa3b, v93
	v_mul_f32_e32 v101, 0xbfb8aa3b, v95
	v_exp_f32_e32 v98, v98
	v_exp_f32_e32 v99, v99
	v_exp_f32_e32 v100, v100
	v_exp_f32_e32 v101, v101
	v_add_f32_e32 v98, 1.0, v98
	v_add_f32_e32 v99, 1.0, v99
	v_add_f32_e32 v100, 1.0, v100
	v_add_f32_e32 v101, 1.0, v101
	v_rcp_f32_e32 v98, v98
	v_rcp_f32_e32 v99, v99
	v_rcp_f32_e32 v100, v100
	v_rcp_f32_e32 v101, v101
	v_pk_mul_f32 v[90:91], v[94:95], v[90:91]
	v_pk_mul_f32 v[88:89], v[92:93], v[88:89]
	v_pk_mul_f32 v[88:89], v[88:89], v[98:99]
	v_pk_mul_f32 v[90:91], v[90:91], v[100:101]
	v_cvt_pk_bf16_f32 v88, v88, v89
	v_cvt_pk_bf16_f32 v89, v90, v91
	v_or_b32_e32 v96, 32, v165
	v_mad_i64_i32 v[96:97], s[14:15], v96, s70, v[142:143]
	v_lshl_add_u64 v[96:97], v[96:97], 0, v[140:141]
	global_store_dwordx2 v[96:97], v[88:89], off
	v_mul_f32_e32 v84, 0xbfb8aa3b, v78
	v_mul_f32_e32 v82, 0xbfb8aa3b, v76
	v_mul_f32_e32 v83, 0xbfb8aa3b, v77
	v_mul_f32_e32 v85, 0xbfb8aa3b, v79
	v_exp_f32_e32 v82, v82
	v_exp_f32_e32 v83, v83
	v_exp_f32_e32 v84, v84
	v_exp_f32_e32 v85, v85
	v_add_f32_e32 v82, 1.0, v82
	v_add_f32_e32 v83, 1.0, v83
	v_add_f32_e32 v84, 1.0, v84
	v_add_f32_e32 v85, 1.0, v85
	v_rcp_f32_e32 v82, v82
	v_rcp_f32_e32 v83, v83
	v_rcp_f32_e32 v84, v84
	v_rcp_f32_e32 v85, v85
	v_pk_mul_f32 v[74:75], v[78:79], v[74:75]
	v_pk_mul_f32 v[72:73], v[76:77], v[72:73]
	v_pk_mul_f32 v[72:73], v[72:73], v[82:83]
	v_pk_mul_f32 v[74:75], v[74:75], v[84:85]
	v_cvt_pk_bf16_f32 v72, v72, v73
	v_cvt_pk_bf16_f32 v73, v74, v75
	v_or_b32_e32 v80, 48, v165
	v_mad_i64_i32 v[80:81], s[14:15], v80, s70, v[142:143]
	v_lshl_add_u64 v[80:81], v[80:81], 0, v[140:141]
	global_store_dwordx2 v[80:81], v[72:73], off
	v_mul_f32_e32 v68, 0xbfb8aa3b, v62
	v_mul_f32_e32 v66, 0xbfb8aa3b, v60
	v_mul_f32_e32 v67, 0xbfb8aa3b, v61
	v_mul_f32_e32 v69, 0xbfb8aa3b, v63
	v_exp_f32_e32 v66, v66
	v_exp_f32_e32 v67, v67
	v_exp_f32_e32 v68, v68
	v_exp_f32_e32 v69, v69
	v_add_f32_e32 v66, 1.0, v66
	v_add_f32_e32 v67, 1.0, v67
	v_add_f32_e32 v68, 1.0, v68
	v_add_f32_e32 v69, 1.0, v69
	v_rcp_f32_e32 v66, v66
	v_rcp_f32_e32 v67, v67
	v_rcp_f32_e32 v68, v68
	v_rcp_f32_e32 v69, v69
	v_pk_mul_f32 v[58:59], v[62:63], v[58:59]
	v_pk_mul_f32 v[56:57], v[60:61], v[56:57]
	v_pk_mul_f32 v[56:57], v[56:57], v[66:67]
	v_pk_mul_f32 v[58:59], v[58:59], v[68:69]
	v_cvt_pk_bf16_f32 v56, v56, v57
	v_cvt_pk_bf16_f32 v57, v58, v59
	v_add_u32_e32 v64, 0x80, v165
	v_mad_i64_i32 v[64:65], s[14:15], v64, s70, v[142:143]
	v_lshl_add_u64 v[64:65], v[64:65], 0, v[140:141]
	global_store_dwordx2 v[64:65], v[56:57], off
	v_mul_f32_e32 v52, 0xbfb8aa3b, v46
	v_mul_f32_e32 v50, 0xbfb8aa3b, v44
	v_mul_f32_e32 v51, 0xbfb8aa3b, v45
	v_mul_f32_e32 v53, 0xbfb8aa3b, v47
	v_exp_f32_e32 v50, v50
	v_exp_f32_e32 v51, v51
	v_exp_f32_e32 v52, v52
	v_exp_f32_e32 v53, v53
	v_add_f32_e32 v50, 1.0, v50
	v_add_f32_e32 v51, 1.0, v51
	v_add_f32_e32 v52, 1.0, v52
	v_add_f32_e32 v53, 1.0, v53
	v_rcp_f32_e32 v50, v50
	v_rcp_f32_e32 v51, v51
	v_rcp_f32_e32 v52, v52
	v_rcp_f32_e32 v53, v53
	v_pk_mul_f32 v[42:43], v[46:47], v[42:43]
	v_pk_mul_f32 v[40:41], v[44:45], v[40:41]
	v_pk_mul_f32 v[40:41], v[40:41], v[50:51]
	v_pk_mul_f32 v[42:43], v[42:43], v[52:53]
	v_cvt_pk_bf16_f32 v40, v40, v41
	v_cvt_pk_bf16_f32 v41, v42, v43
	v_add_u32_e32 v48, 0x90, v165
	v_mad_i64_i32 v[48:49], s[14:15], v48, s70, v[142:143]
	v_lshl_add_u64 v[48:49], v[48:49], 0, v[140:141]
	global_store_dwordx2 v[48:49], v[40:41], off
	v_mul_f32_e32 v36, 0xbfb8aa3b, v30
	v_mul_f32_e32 v34, 0xbfb8aa3b, v28
	v_mul_f32_e32 v35, 0xbfb8aa3b, v29
	v_mul_f32_e32 v37, 0xbfb8aa3b, v31
	v_exp_f32_e32 v34, v34
	v_exp_f32_e32 v35, v35
	v_exp_f32_e32 v36, v36
	v_exp_f32_e32 v37, v37
	v_add_f32_e32 v34, 1.0, v34
	v_add_f32_e32 v35, 1.0, v35
	v_add_f32_e32 v36, 1.0, v36
	v_add_f32_e32 v37, 1.0, v37
	v_rcp_f32_e32 v34, v34
	v_rcp_f32_e32 v35, v35
	v_rcp_f32_e32 v36, v36
	v_rcp_f32_e32 v37, v37
	v_pk_mul_f32 v[26:27], v[30:31], v[26:27]
	v_pk_mul_f32 v[24:25], v[28:29], v[24:25]
	v_pk_mul_f32 v[24:25], v[24:25], v[34:35]
	v_pk_mul_f32 v[26:27], v[26:27], v[36:37]
	v_cvt_pk_bf16_f32 v24, v24, v25
	v_cvt_pk_bf16_f32 v25, v26, v27
	v_add_u32_e32 v32, 0xa0, v165
	v_mad_i64_i32 v[32:33], s[14:15], v32, s70, v[142:143]
	v_lshl_add_u64 v[32:33], v[32:33], 0, v[140:141]
	global_store_dwordx2 v[32:33], v[24:25], off
	v_mul_f32_e32 v20, 0xbfb8aa3b, v14
	v_mul_f32_e32 v18, 0xbfb8aa3b, v12
	v_mul_f32_e32 v19, 0xbfb8aa3b, v13
	v_mul_f32_e32 v21, 0xbfb8aa3b, v15
	v_exp_f32_e32 v18, v18
	v_exp_f32_e32 v19, v19
	v_exp_f32_e32 v20, v20
	v_exp_f32_e32 v21, v21
	v_add_f32_e32 v18, 1.0, v18
	v_add_f32_e32 v19, 1.0, v19
	v_add_f32_e32 v20, 1.0, v20
	v_add_f32_e32 v21, 1.0, v21
	v_rcp_f32_e32 v18, v18
	v_rcp_f32_e32 v19, v19
	v_rcp_f32_e32 v20, v20
	v_rcp_f32_e32 v21, v21
	v_pk_mul_f32 v[10:11], v[14:15], v[10:11]
	v_pk_mul_f32 v[8:9], v[12:13], v[8:9]
	v_pk_mul_f32 v[8:9], v[8:9], v[18:19]
	v_pk_mul_f32 v[10:11], v[10:11], v[20:21]
	v_cvt_pk_bf16_f32 v8, v8, v9
	v_cvt_pk_bf16_f32 v9, v10, v11
	v_add_u32_e32 v16, 0xb0, v165
	v_mad_i64_i32 v[16:17], s[14:15], v16, s70, v[142:143]
	v_lshl_add_u64 v[16:17], v[16:17], 0, v[140:141]
	global_store_dwordx2 v[16:17], v[8:9], off
	s_and_b64 vcc, exec, s[2:3]
	s_mov_b32 s74, s71
	s_mov_b32 s73, s72
	s_mov_b64 s[16:17], s[0:1]
	s_mov_b64 s[14:15], s[4:5]

; #define PG8_STAGE(bufoff, gbase, voff) do { _Pragma("unroll") for (int _i = 0; _i < 2; ++_i) \
;         __builtin_amdgcn_global_load_lds((const unsigned*)((const char*)(gbase) + (voff)[_i]), (PG8_LAS unsigned*)(lds + (bufoff) + ldsw + _i * 8192), 16, 0, 0); } while (0)
; #define PG8_LDA(dst, b, h) do { _Pragma("unroll") for (int m = 0; m < 4; ++m) _Pragma("unroll") for (int k = 0; k < 2; ++k) dst[m][k] = *(const PG8_LAS bf16x8*)(lds + PG8_SA(b, h) + aoff + m * 2048 + k * 1024); } while (0)
; #define PG8_LDB(dst, b, h) do { _Pragma("unroll") for (int n = 0; n < 2; ++n) _Pragma("unroll") for (int k = 0; k < 2; ++k) dst[n][k] = *(const PG8_LAS bf16x8*)(lds + PG8_SB(b, h) + boff + n * 2048 + k * 1024); } while (0)
; #define PG8_WAIT_V(n) asm volatile("s_waitcnt vmcnt(" #n ")" ::: "memory")
; #define PG8_WAIT_L(n) asm volatile("s_waitcnt lgkmcnt(" #n ")" ::: "memory")
; #define PG8_BAR __builtin_amdgcn_s_barrier()
; #define PG8_SCHED __builtin_amdgcn_sched_barrier(0)
; template <class Epi, class Sched, bool STAMP = false>
; __device__ __forceinline__ void gemm_phase(PG8_LAS unsigned char* lds, const Gemm g, const Sched& S, const Epi& E, unsigned long long* stamps) {
;     ...
;         for (int t = 0; t < nt; t += 2) {
;             const bool last = (t == nt - 2);
;             const char* a1 = cA + (size_t)(t + 1) * kstep;
;             const char* a2 = last ? nA : cA + (size_t)(t + 2) * kstep; const char* b2 = last ? nB : cB + (size_t)(t + 2) * kstep;
;             const char* a3 = a2 + kstep; const char* b3 = b2 + kstep;
;             if (last && has_next) S.a_ready(nxt);
;             PG8_LDB(B0, 0, 0); PG8_SCHED; PG8_LDA(At, 0, 0); PG8_STAGE(PG8_SA(1, 1), a1 + hstep, voffA);
;             PG8_WAIT_L(8); PG8_BAR; PG8_WAIT_L(0); PG8_MMA(0, 0, At, B0); PG8_BAR; PG8_SCHED;
;             PG8_LDB(B1, 0, 1); PG8_STAGE(PG8_SB(0, 0), b2, voffB);
;             PG8_BAR; PG8_WAIT_L(0); PG8_MMA(0, 1, At, B1); PG8_BAR;
;             PG8_LDA(At, 0, 1); PG8_STAGE(PG8_SA(0, 0), a2, voffA);
;             PG8_BAR; PG8_WAIT_L(0); PG8_MMA(1, 0, At, B0); PG8_BAR; PG8_SCHED;
;             PG8_STAGE(PG8_SB(0, 1), b2 + hstep, voffB);
;             PG8_WAIT_V(6); PG8_BAR; PG8_MMA(1, 1, At, B1); PG8_BAR;
;             PG8_LDB(B0, 1, 0); PG8_SCHED; PG8_LDA(At, 1, 0); PG8_STAGE(PG8_SA(0, 1), a2 + hstep, voffA);
.Lgu2_half_loop:
	ds_read_b128 v[140:143], v147
	ds_read_b128 v[170:173], v148
	ds_read_b128 v[174:177], v149
	ds_read_b128 v[178:181], v150
	s_add_u32 s36, s34, 0x100
	s_addc_u32 s37, s35, 0
	s_cmp_eq_u32 s89, 12
	s_cselect_b32 s55, s5, s37
	s_cselect_b32 s54, s4, s36
	s_cselect_b32 s53, s1, s88
	s_cselect_b32 s52, s0, s87
	s_mov_b32 m0, s78
	v_lshl_add_u64 v[214:215], s[34:35], 0, v[132:133]
	ds_read_b128 v[182:185], v145
	ds_read_b128 v[186:189], v145 offset:1024
	ds_read_b128 v[190:193], v145 offset:2048
	ds_read_b128 v[194:197], v145 offset:3072
	ds_read_b128 v[198:201], v145 offset:4096
	ds_read_b128 v[202:205], v145 offset:5120
	ds_read_b128 v[206:209], v145 offset:6144
	ds_read_b128 v[210:213], v145 offset:7168
	global_load_lds_dwordx4 v[214:215], off
	v_lshl_add_u64 v[214:215], s[34:35], 0, v[134:135]
	s_mov_b32 m0, s79
	s_nop 0
	global_load_lds_dwordx4 v[214:215], off
	s_waitcnt lgkmcnt(8)
	s_barrier
	s_waitcnt lgkmcnt(0)
	s_setprio 1
	s_waitcnt lgkmcnt(0)
	v_mfma_f32_16x16x32_bf16 v[124:127], v[140:143], v[182:185], v[124:127]
	v_mfma_f32_16x16x32_bf16 v[120:123], v[174:177], v[182:185], v[120:123]
	v_mfma_f32_16x16x32_bf16 v[108:111], v[140:143], v[190:193], v[108:111]
	v_mfma_f32_16x16x32_bf16 v[104:107], v[174:177], v[190:193], v[104:107]
	v_mfma_f32_16x16x32_bf16 v[92:95], v[140:143], v[198:201], v[92:95]
	v_mfma_f32_16x16x32_bf16 v[88:91], v[174:177], v[198:201], v[88:91]
	v_mfma_f32_16x16x32_bf16 v[76:79], v[140:143], v[206:209], v[76:79]
	v_mfma_f32_16x16x32_bf16 v[72:75], v[174:177], v[206:209], v[72:75]
	v_mfma_f32_16x16x32_bf16 v[124:127], v[170:173], v[186:189], v[124:127]
	v_mfma_f32_16x16x32_bf16 v[120:123], v[178:181], v[186:189], v[120:123]
	v_mfma_f32_16x16x32_bf16 v[108:111], v[170:173], v[194:197], v[108:111]
	v_mfma_f32_16x16x32_bf16 v[104:107], v[178:181], v[194:197], v[104:107]
	v_mfma_f32_16x16x32_bf16 v[92:95], v[170:173], v[202:205], v[92:95]
	v_mfma_f32_16x16x32_bf16 v[88:91], v[178:181], v[202:205], v[88:91]
	v_mfma_f32_16x16x32_bf16 v[76:79], v[170:173], v[210:213], v[76:79]
	v_mfma_f32_16x16x32_bf16 v[72:75], v[178:181], v[210:213], v[72:75]
	s_setprio 0
	s_barrier
	s_mov_b32 m0, s61
	v_lshl_add_u64 v[230:231], s[52:53], 0, v[130:131]
	global_load_lds_dwordx4 v[230:231], off
	v_lshl_add_u64 v[232:233], s[52:53], 0, v[128:129]
	s_mov_b32 m0, s62
	s_nop 0
	global_load_lds_dwordx4 v[232:233], off
	s_barrier
	s_waitcnt lgkmcnt(0)
	s_setprio 1
	s_waitcnt lgkmcnt(0)
	s_setprio 0
	s_mov_b32 m0, s58
	v_lshl_add_u64 v[234:235], s[54:55], 0, v[130:131]
	s_barrier
	ds_read_b128 v[182:185], v145 offset:16384
	ds_read_b128 v[186:189], v145 offset:17408
	ds_read_b128 v[190:193], v145 offset:18432
	ds_read_b128 v[194:197], v145 offset:19456
	ds_read_b128 v[198:201], v145 offset:20480
	ds_read_b128 v[202:205], v145 offset:21504
	ds_read_b128 v[206:209], v145 offset:22528
	ds_read_b128 v[210:213], v145 offset:23552
	global_load_lds_dwordx4 v[234:235], off
	v_lshl_add_u64 v[236:237], s[54:55], 0, v[128:129]
	s_mov_b32 m0, s63
	s_nop 0
	global_load_lds_dwordx4 v[236:237], off
	s_barrier
	s_waitcnt lgkmcnt(0)
	s_setprio 1
	s_waitcnt lgkmcnt(0)
	v_mfma_f32_16x16x32_bf16 v[60:63], v[140:143], v[182:185], v[60:63]
	v_mfma_f32_16x16x32_bf16 v[56:59], v[174:177], v[182:185], v[56:59]
	v_mfma_f32_16x16x32_bf16 v[44:47], v[140:143], v[190:193], v[44:47]
	v_mfma_f32_16x16x32_bf16 v[40:43], v[174:177], v[190:193], v[40:43]
	v_mfma_f32_16x16x32_bf16 v[28:31], v[140:143], v[198:201], v[28:31]
	v_mfma_f32_16x16x32_bf16 v[24:27], v[174:177], v[198:201], v[24:27]
	v_mfma_f32_16x16x32_bf16 v[12:15], v[140:143], v[206:209], v[12:15]
	v_mfma_f32_16x16x32_bf16 v[8:11], v[174:177], v[206:209], v[8:11]
	v_mfma_f32_16x16x32_bf16 v[60:63], v[170:173], v[186:189], v[60:63]
	v_mfma_f32_16x16x32_bf16 v[56:59], v[178:181], v[186:189], v[56:59]
	v_mfma_f32_16x16x32_bf16 v[44:47], v[170:173], v[194:197], v[44:47]
	v_mfma_f32_16x16x32_bf16 v[40:43], v[178:181], v[194:197], v[40:43]
	v_mfma_f32_16x16x32_bf16 v[28:31], v[170:173], v[202:205], v[28:31]
	v_mfma_f32_16x16x32_bf16 v[24:27], v[178:181], v[202:205], v[24:27]
	v_mfma_f32_16x16x32_bf16 v[12:15], v[170:173], v[210:213], v[12:15]
	v_mfma_f32_16x16x32_bf16 v[8:11], v[178:181], v[210:213], v[8:11]
	s_setprio 0
	s_barrier
	s_add_u32 s34, s52, 0x44000
	s_addc_u32 s35, s53, 0
	s_mov_b32 m0, s64
	v_lshl_add_u64 v[140:141], s[34:35], 0, v[130:131]
	global_load_lds_dwordx4 v[140:141], off
	v_lshl_add_u64 v[140:141], s[34:35], 0, v[128:129]
	s_mov_b32 m0, s65
	s_nop 0
	global_load_lds_dwordx4 v[140:141], off
	s_waitcnt vmcnt(6)
	s_barrier
	s_setprio 1
	s_setprio 0
	s_barrier
	ds_read_b128 v[140:143], v155
	ds_read_b128 v[170:173], v156
	ds_read_b128 v[174:177], v157
	ds_read_b128 v[178:181], v165
	s_add_u32 s34, s54, 0x44000
	s_addc_u32 s35, s55, 0
	s_mov_b32 m0, s66
	v_lshl_add_u64 v[214:215], s[34:35], 0, v[130:131]
	ds_read_b128 v[182:185], v145 offset:32768
	ds_read_b128 v[186:189], v145 offset:33792
	ds_read_b128 v[190:193], v145 offset:34816
	ds_read_b128 v[194:197], v145 offset:35840
	ds_read_b128 v[198:201], v145 offset:36864
	ds_read_b128 v[202:205], v145 offset:37888
	ds_read_b128 v[206:209], v145 offset:38912
	ds_read_b128 v[210:213], v145 offset:39936
	global_load_lds_dwordx4 v[214:215], off
	v_lshl_add_u64 v[214:215], s[34:35], 0, v[128:129]
	s_mov_b32 m0, s67
	s_nop 0
	global_load_lds_dwordx4 v[214:215], off
	s_waitcnt lgkmcnt(8)
	s_barrier
; DI float ex2(float x) { return __builtin_amdgcn_exp2f(x); }
; #define PG8_STAGE(bufoff, gbase, voff) do { _Pragma("unroll") for (int _i = 0; _i < 2; ++_i) \
;         __builtin_amdgcn_global_load_lds((const unsigned*)((const char*)(gbase) + (voff)[_i]), (PG8_LAS unsigned*)(lds + (bufoff) + ldsw + _i * 8192), 16, 0, 0); } while (0)
; #define PG8_LDA(dst, b, h) do { _Pragma("unroll") for (int m = 0; m < 4; ++m) _Pragma("unroll") for (int k = 0; k < 2; ++k) dst[m][k] = *(const PG8_LAS bf16x8*)(lds + PG8_SA(b, h) + aoff + m * 2048 + k * 1024); } while (0)
; #define PG8_WAIT_V(n) asm volatile("s_waitcnt vmcnt(" #n ")" ::: "memory")
; #define PG8_WAIT_L(n) asm volatile("s_waitcnt lgkmcnt(" #n ")" ::: "memory")
; #define PG8_BAR __builtin_amdgcn_s_barrier()
;     DI void operator()(const f32x4 (&acc)[2][2][4][2], const Unit& u, int wr, int wc, int fr, int fq) const {
;         const int row0 = u.pm * BM + wr * 64 + fr, hcol0 = ((u.pn * BM + wc * 32) >> 1) + 4 * fq;
; #pragma unroll
;         for (int ai = 0; ai < 2; ++ai)
; #pragma unroll
;             for (int m = 0; m < 4; ++m) { u16* rowp = O + (size_t)(row0 + ai * HALF + m * 16) * ldc + hcol0;
; #pragma unroll
;                 for (int bj = 0; bj < 2; ++bj) { const f32x4 g = acc[ai][bj][m][0], up = acc[ai][bj][m][1]; float r[4];
; #pragma unroll
;                     for (int j = 0; j < 4; ++j) r[j] = g[j] * up[j] * __builtin_amdgcn_rcpf(1.f + ex2(-LOG2E * g[j]));
;                     uint2 w = {pack2(r[0], r[1]), pack2(r[2], r[3])}; *(uint2*)(rowp + bj * (HALF / 2)) = w; } }
; template <class Epi, class Sched, bool STAMP = false>
; __device__ __forceinline__ void gemm_phase(PG8_LAS unsigned char* lds, const Gemm g, const Sched& S, const Epi& E, unsigned long long* stamps) {
;     ...
;             PG8_LDB(B0, 1, 0); PG8_SCHED; PG8_LDA(At, 1, 0); PG8_STAGE(PG8_SA(0, 1), a2 + hstep, voffA);
;             PG8_WAIT_L(8); PG8_BAR; PG8_WAIT_L(0); PG8_MMA(0, 0, At, B0); PG8_BAR; PG8_SCHED;
;             PG8_LDB(B1, 1, 1); PG8_STAGE(PG8_SB(1, 0), b3, voffB);
;             PG8_BAR; PG8_WAIT_L(0); PG8_MMA(0, 1, At, B1); PG8_BAR;
;             PG8_LDA(At, 1, 1); PG8_STAGE(PG8_SA(1, 0), a3, voffA);
;             PG8_BAR; PG8_WAIT_L(0); PG8_MMA(1, 0, At, B0); PG8_BAR; PG8_SCHED;
;             PG8_STAGE(PG8_SB(1, 1), b3 + hstep, voffB);
;             PG8_WAIT_V(6); PG8_BAR; PG8_MMA(1, 1, At, B1); PG8_BAR;
;         }
	s_waitcnt lgkmcnt(0)
	s_setprio 1
	s_waitcnt lgkmcnt(0)
	v_mfma_f32_16x16x32_bf16 v[124:127], v[140:143], v[182:185], v[124:127]
	v_mfma_f32_16x16x32_bf16 v[120:123], v[174:177], v[182:185], v[120:123]
	v_mfma_f32_16x16x32_bf16 v[108:111], v[140:143], v[190:193], v[108:111]
	v_mfma_f32_16x16x32_bf16 v[104:107], v[174:177], v[190:193], v[104:107]
	v_mfma_f32_16x16x32_bf16 v[92:95], v[140:143], v[198:201], v[92:95]
	v_mfma_f32_16x16x32_bf16 v[88:91], v[174:177], v[198:201], v[88:91]
	v_mfma_f32_16x16x32_bf16 v[76:79], v[140:143], v[206:209], v[76:79]
	v_mfma_f32_16x16x32_bf16 v[72:75], v[174:177], v[206:209], v[72:75]
	v_mfma_f32_16x16x32_bf16 v[124:127], v[170:173], v[186:189], v[124:127]
	v_mfma_f32_16x16x32_bf16 v[120:123], v[178:181], v[186:189], v[120:123]
	v_mfma_f32_16x16x32_bf16 v[108:111], v[170:173], v[194:197], v[108:111]
	v_mfma_f32_16x16x32_bf16 v[104:107], v[178:181], v[194:197], v[104:107]
	v_mfma_f32_16x16x32_bf16 v[92:95], v[170:173], v[202:205], v[92:95]
	v_mfma_f32_16x16x32_bf16 v[88:91], v[178:181], v[202:205], v[88:91]
	v_mfma_f32_16x16x32_bf16 v[76:79], v[170:173], v[210:213], v[76:79]
	v_mfma_f32_16x16x32_bf16 v[72:75], v[178:181], v[210:213], v[72:75]
	s_setprio 0
	s_barrier
	s_mov_b32 m0, s70
	v_lshl_add_u64 v[230:231], v[230:231], 0, s[6:7]
	global_load_lds_dwordx4 v[230:231], off
	v_lshl_add_u64 v[230:231], v[232:233], 0, s[6:7]
	s_mov_b32 m0, s71
	s_nop 0
	global_load_lds_dwordx4 v[230:231], off
	s_barrier
	s_waitcnt lgkmcnt(0)
	s_setprio 1
	s_waitcnt lgkmcnt(0)
	s_setprio 0
	s_mov_b32 m0, s73
	v_lshl_add_u64 v[230:231], v[234:235], 0, s[6:7]
	s_barrier
	ds_read_b128 v[182:185], v145 offset:49152
	ds_read_b128 v[186:189], v145 offset:50176
	ds_read_b128 v[190:193], v145 offset:51200
	ds_read_b128 v[194:197], v145 offset:52224
	ds_read_b128 v[198:201], v145 offset:53248
	ds_read_b128 v[202:205], v145 offset:54272
	ds_read_b128 v[206:209], v145 offset:55296
	ds_read_b128 v[210:213], v145 offset:56320
	global_load_lds_dwordx4 v[230:231], off
	v_lshl_add_u64 v[230:231], v[236:237], 0, s[6:7]
	s_mov_b32 m0, s74
	s_nop 0
	global_load_lds_dwordx4 v[230:231], off
	s_barrier
	s_waitcnt lgkmcnt(0)
	s_setprio 1
	s_waitcnt lgkmcnt(0)
	v_mfma_f32_16x16x32_bf16 v[60:63], v[140:143], v[182:185], v[60:63]
	v_mfma_f32_16x16x32_bf16 v[56:59], v[174:177], v[182:185], v[56:59]
	v_mfma_f32_16x16x32_bf16 v[44:47], v[140:143], v[190:193], v[44:47]
	v_mfma_f32_16x16x32_bf16 v[40:43], v[174:177], v[190:193], v[40:43]
	v_mfma_f32_16x16x32_bf16 v[28:31], v[140:143], v[198:201], v[28:31]
	v_mfma_f32_16x16x32_bf16 v[24:27], v[174:177], v[198:201], v[24:27]
	v_mfma_f32_16x16x32_bf16 v[12:15], v[140:143], v[206:209], v[12:15]
	v_mfma_f32_16x16x32_bf16 v[8:11], v[174:177], v[206:209], v[8:11]
	v_mfma_f32_16x16x32_bf16 v[60:63], v[170:173], v[186:189], v[60:63]
	v_mfma_f32_16x16x32_bf16 v[56:59], v[178:181], v[186:189], v[56:59]
	v_mfma_f32_16x16x32_bf16 v[44:47], v[170:173], v[194:197], v[44:47]
	v_mfma_f32_16x16x32_bf16 v[40:43], v[178:181], v[194:197], v[40:43]
	v_mfma_f32_16x16x32_bf16 v[28:31], v[170:173], v[202:205], v[28:31]
	v_mfma_f32_16x16x32_bf16 v[24:27], v[178:181], v[202:205], v[24:27]
	v_mfma_f32_16x16x32_bf16 v[12:15], v[170:173], v[210:213], v[12:15]
	v_mfma_f32_16x16x32_bf16 v[8:11], v[178:181], v[210:213], v[8:11]
	s_setprio 0
	s_barrier
	s_add_u32 s34, s52, 0x44080
	s_addc_u32 s35, s53, 0
	s_mov_b32 m0, s75
	v_lshl_add_u64 v[140:141], s[34:35], 0, v[130:131]
	global_load_lds_dwordx4 v[140:141], off
	v_lshl_add_u64 v[140:141], s[34:35], 0, v[128:129]
	s_mov_b32 m0, s76
	s_nop 0
	global_load_lds_dwordx4 v[140:141], off
	s_waitcnt vmcnt(6)
	s_barrier
	s_setprio 1
	s_setprio 0
	s_add_i32 s89, s89, 2
	s_add_u32 s87, s87, 0x100
	s_addc_u32 s88, s88, 0
	s_cmp_gt_u32 s89, 13
	s_mov_b64 s[34:35], s[36:37]
	s_barrier
	s_cbranch_scc0 .Lgu2_half_loop
	v_mul_f32_e32 v171, 0xbfb8aa3b, v124
	v_exp_f32_e32 v171, v171
	v_mul_f32_e32 v174, 0xbfb8aa3b, v125
	v_exp_f32_e32 v175, v174
	s_lshl_b32 s10, s86, 8
	v_add_f32_e32 v171, 1.0, v171
	v_rcp_f32_e32 v174, v171
	v_add_f32_e32 v171, 1.0, v175
	v_mul_f32_e32 v175, 0xbfb8aa3b, v126
	v_exp_f32_e32 v176, v175
	v_mul_f32_e32 v175, 0xbfb8aa3b, v127
	v_exp_f32_e32 v177, v175
	v_rcp_f32_e32 v175, v171
	v_add_f32_e32 v171, 1.0, v176
	v_rcp_f32_e32 v176, v171
	v_add_f32_e32 v171, 1.0, v177
	v_rcp_f32_e32 v177, v171
	v_pk_mul_f32 v[122:123], v[126:127], v[122:123]
	v_pk_mul_f32 v[120:121], v[124:125], v[120:121]
	s_or_b32 s10, s10, s69
	s_or_b32 s10, s10, s98
	v_pk_mul_f32 v[120:121], v[120:121], v[174:175]
	v_pk_mul_f32 v[122:123], v[122:123], v[176:177]
	s_ashr_i32 s10, s10, 1
	v_cvt_pk_bf16_f32 v120, v120, v121
	v_cvt_pk_bf16_f32 v121, v122, v123
	v_or_b32_e32 v140, s10, v146
	v_lshl_add_u32 v170, s85, 8, v144
	v_ashrrev_i32_e32 v141, 31, v140
	v_mov_b64_e32 v[142:143], s[12:13]
	v_mad_i64_i32 v[172:173], s[34:35], v170, s82, v[142:143]
	v_lshlrev_b64 v[140:141], 1, v[140:141]
	v_lshl_add_u64 v[172:173], v[172:173], 0, v[140:141]
	global_store_dwordx2 v[172:173], v[120:121], off
	v_mul_f32_e32 v116, 0xbfb8aa3b, v110
	v_mul_f32_e32 v114, 0xbfb8aa3b, v108
	v_mul_f32_e32 v115, 0xbfb8aa3b, v109
	v_mul_f32_e32 v117, 0xbfb8aa3b, v111
	v_exp_f32_e32 v114, v114
	v_exp_f32_e32 v115, v115
	v_exp_f32_e32 v116, v116
	v_exp_f32_e32 v117, v117
	v_add_f32_e32 v114, 1.0, v114
	v_add_f32_e32 v115, 1.0, v115
	v_add_f32_e32 v116, 1.0, v116
	v_add_f32_e32 v117, 1.0, v117
	v_rcp_f32_e32 v114, v114
	v_rcp_f32_e32 v115, v115
	v_rcp_f32_e32 v116, v116
	v_rcp_f32_e32 v117, v117
	v_pk_mul_f32 v[106:107], v[110:111], v[106:107]
	v_pk_mul_f32 v[104:105], v[108:109], v[104:105]
	v_pk_mul_f32 v[104:105], v[104:105], v[114:115]
; DI float ex2(float x) { return __builtin_amdgcn_exp2f(x); }
;     DI void operator()(const f32x4 (&acc)[2][2][4][2], const Unit& u, int wr, int wc, int fr, int fq) const {
;         const int row0 = u.pm * BM + wr * 64 + fr, hcol0 = ((u.pn * BM + wc * 32) >> 1) + 4 * fq;
; #pragma unroll
;         for (int ai = 0; ai < 2; ++ai)
; #pragma unroll
;             for (int m = 0; m < 4; ++m) { u16* rowp = O + (size_t)(row0 + ai * HALF + m * 16) * ldc + hcol0;
; #pragma unroll
;                 for (int bj = 0; bj < 2; ++bj) { const f32x4 g = acc[ai][bj][m][0], up = acc[ai][bj][m][1]; float r[4];
; #pragma unroll
;                     for (int j = 0; j < 4; ++j) r[j] = g[j] * up[j] * __builtin_amdgcn_rcpf(1.f + ex2(-LOG2E * g[j]));
;                     uint2 w = {pack2(r[0], r[1]), pack2(r[2], r[3])}; *(uint2*)(rowp + bj * (HALF / 2)) = w; } }
	v_pk_mul_f32 v[106:107], v[106:107], v[116:117]
	v_cvt_pk_bf16_f32 v104, v104, v105
	v_cvt_pk_bf16_f32 v105, v106, v107
	v_or_b32_e32 v112, 16, v170
	v_mad_i64_i32 v[112:113], s[34:35], v112, s82, v[142:143]
	v_lshl_add_u64 v[112:113], v[112:113], 0, v[140:141]
	global_store_dwordx2 v[112:113], v[104:105], off
	v_mul_f32_e32 v100, 0xbfb8aa3b, v94
	v_mul_f32_e32 v98, 0xbfb8aa3b, v92
	v_mul_f32_e32 v99, 0xbfb8aa3b, v93
	v_mul_f32_e32 v101, 0xbfb8aa3b, v95
	v_exp_f32_e32 v98, v98
	v_exp_f32_e32 v99, v99
	v_exp_f32_e32 v100, v100
	v_exp_f32_e32 v101, v101
	v_add_f32_e32 v98, 1.0, v98
	v_add_f32_e32 v99, 1.0, v99
	v_add_f32_e32 v100, 1.0, v100
	v_add_f32_e32 v101, 1.0, v101
	v_rcp_f32_e32 v98, v98
	v_rcp_f32_e32 v99, v99
	v_rcp_f32_e32 v100, v100
	v_rcp_f32_e32 v101, v101
	v_pk_mul_f32 v[90:91], v[94:95], v[90:91]
	v_pk_mul_f32 v[88:89], v[92:93], v[88:89]
	v_pk_mul_f32 v[88:89], v[88:89], v[98:99]
	v_pk_mul_f32 v[90:91], v[90:91], v[100:101]
	v_cvt_pk_bf16_f32 v88, v88, v89
	v_cvt_pk_bf16_f32 v89, v90, v91
	v_or_b32_e32 v96, 32, v170
	v_mad_i64_i32 v[96:97], s[34:35], v96, s82, v[142:143]
	v_lshl_add_u64 v[96:97], v[96:97], 0, v[140:141]
	global_store_dwordx2 v[96:97], v[88:89], off
	v_mul_f32_e32 v84, 0xbfb8aa3b, v78
	v_mul_f32_e32 v82, 0xbfb8aa3b, v76
	v_mul_f32_e32 v83, 0xbfb8aa3b, v77
	v_mul_f32_e32 v85, 0xbfb8aa3b, v79
	v_exp_f32_e32 v82, v82
	v_exp_f32_e32 v83, v83
	v_exp_f32_e32 v84, v84
	v_exp_f32_e32 v85, v85
	v_add_f32_e32 v82, 1.0, v82
	v_add_f32_e32 v83, 1.0, v83
	v_add_f32_e32 v84, 1.0, v84
	v_add_f32_e32 v85, 1.0, v85
	v_rcp_f32_e32 v82, v82
	v_rcp_f32_e32 v83, v83
	v_rcp_f32_e32 v84, v84
	v_rcp_f32_e32 v85, v85
	v_pk_mul_f32 v[74:75], v[78:79], v[74:75]
	v_pk_mul_f32 v[72:73], v[76:77], v[72:73]
	v_pk_mul_f32 v[72:73], v[72:73], v[82:83]
	v_pk_mul_f32 v[74:75], v[74:75], v[84:85]
	v_cvt_pk_bf16_f32 v72, v72, v73
	v_cvt_pk_bf16_f32 v73, v74, v75
	v_or_b32_e32 v80, 48, v170
	v_mad_i64_i32 v[80:81], s[34:35], v80, s82, v[142:143]
	v_lshl_add_u64 v[80:81], v[80:81], 0, v[140:141]
	global_store_dwordx2 v[80:81], v[72:73], off
	v_mul_f32_e32 v68, 0xbfb8aa3b, v62
	v_mul_f32_e32 v66, 0xbfb8aa3b, v60
	v_mul_f32_e32 v67, 0xbfb8aa3b, v61
	v_mul_f32_e32 v69, 0xbfb8aa3b, v63
	v_exp_f32_e32 v66, v66
	v_exp_f32_e32 v67, v67
	v_exp_f32_e32 v68, v68
	v_exp_f32_e32 v69, v69
	v_add_f32_e32 v66, 1.0, v66
	v_add_f32_e32 v67, 1.0, v67
	v_add_f32_e32 v68, 1.0, v68
	v_add_f32_e32 v69, 1.0, v69
	v_rcp_f32_e32 v66, v66
	v_rcp_f32_e32 v67, v67
	v_rcp_f32_e32 v68, v68
	v_rcp_f32_e32 v69, v69
	v_pk_mul_f32 v[58:59], v[62:63], v[58:59]
	v_pk_mul_f32 v[56:57], v[60:61], v[56:57]
	v_pk_mul_f32 v[56:57], v[56:57], v[66:67]
	v_pk_mul_f32 v[58:59], v[58:59], v[68:69]
	v_cvt_pk_bf16_f32 v56, v56, v57
	v_cvt_pk_bf16_f32 v57, v58, v59
	v_add_u32_e32 v64, 0x80, v170
	v_mad_i64_i32 v[64:65], s[34:35], v64, s82, v[142:143]
	v_lshl_add_u64 v[64:65], v[64:65], 0, v[140:141]
	global_store_dwordx2 v[64:65], v[56:57], off
	v_mul_f32_e32 v52, 0xbfb8aa3b, v46
	v_mul_f32_e32 v50, 0xbfb8aa3b, v44
	v_mul_f32_e32 v51, 0xbfb8aa3b, v45
	v_mul_f32_e32 v53, 0xbfb8aa3b, v47
	v_exp_f32_e32 v50, v50
	v_exp_f32_e32 v51, v51
	v_exp_f32_e32 v52, v52
	v_exp_f32_e32 v53, v53
	v_add_f32_e32 v50, 1.0, v50
	v_add_f32_e32 v51, 1.0, v51
	v_add_f32_e32 v52, 1.0, v52
	v_add_f32_e32 v53, 1.0, v53
	v_rcp_f32_e32 v50, v50
	v_rcp_f32_e32 v51, v51
	v_rcp_f32_e32 v52, v52
	v_rcp_f32_e32 v53, v53
	v_pk_mul_f32 v[42:43], v[46:47], v[42:43]
	v_pk_mul_f32 v[40:41], v[44:45], v[40:41]
	v_pk_mul_f32 v[40:41], v[40:41], v[50:51]
	v_pk_mul_f32 v[42:43], v[42:43], v[52:53]
	v_cvt_pk_bf16_f32 v40, v40, v41
	v_cvt_pk_bf16_f32 v41, v42, v43
	v_add_u32_e32 v48, 0x90, v170
	v_mad_i64_i32 v[48:49], s[34:35], v48, s82, v[142:143]
	v_lshl_add_u64 v[48:49], v[48:49], 0, v[140:141]
	global_store_dwordx2 v[48:49], v[40:41], off
	v_mul_f32_e32 v36, 0xbfb8aa3b, v30
	v_mul_f32_e32 v34, 0xbfb8aa3b, v28
	v_mul_f32_e32 v35, 0xbfb8aa3b, v29
	v_mul_f32_e32 v37, 0xbfb8aa3b, v31
	v_exp_f32_e32 v34, v34
	v_exp_f32_e32 v35, v35
	v_exp_f32_e32 v36, v36
	v_exp_f32_e32 v37, v37
	v_add_f32_e32 v34, 1.0, v34
	v_add_f32_e32 v35, 1.0, v35
	v_add_f32_e32 v36, 1.0, v36
	v_add_f32_e32 v37, 1.0, v37
	v_rcp_f32_e32 v34, v34
	v_rcp_f32_e32 v35, v35
	v_rcp_f32_e32 v36, v36
	v_rcp_f32_e32 v37, v37
	v_pk_mul_f32 v[26:27], v[30:31], v[26:27]
	v_pk_mul_f32 v[24:25], v[28:29], v[24:25]
	v_pk_mul_f32 v[24:25], v[24:25], v[34:35]
	v_pk_mul_f32 v[26:27], v[26:27], v[36:37]
	v_cvt_pk_bf16_f32 v24, v24, v25
	v_cvt_pk_bf16_f32 v25, v26, v27
	v_add_u32_e32 v32, 0xa0, v170
	v_mad_i64_i32 v[32:33], s[34:35], v32, s82, v[142:143]
	v_lshl_add_u64 v[32:33], v[32:33], 0, v[140:141]
	global_store_dwordx2 v[32:33], v[24:25], off
	v_mul_f32_e32 v20, 0xbfb8aa3b, v14
	v_mul_f32_e32 v18, 0xbfb8aa3b, v12
	v_mul_f32_e32 v19, 0xbfb8aa3b, v13
	v_mul_f32_e32 v21, 0xbfb8aa3b, v15
	v_exp_f32_e32 v18, v18
	v_exp_f32_e32 v19, v19
	v_exp_f32_e32 v20, v20
	v_exp_f32_e32 v21, v21
	v_add_f32_e32 v18, 1.0, v18
	v_add_f32_e32 v19, 1.0, v19
	v_add_f32_e32 v20, 1.0, v20
	v_add_f32_e32 v21, 1.0, v21
	v_rcp_f32_e32 v18, v18
	v_rcp_f32_e32 v19, v19
	v_rcp_f32_e32 v20, v20
	v_rcp_f32_e32 v21, v21
	v_pk_mul_f32 v[10:11], v[14:15], v[10:11]
	v_pk_mul_f32 v[8:9], v[12:13], v[8:9]
	v_pk_mul_f32 v[8:9], v[8:9], v[18:19]
	v_pk_mul_f32 v[10:11], v[10:11], v[20:21]
	v_cvt_pk_bf16_f32 v8, v8, v9
	v_cvt_pk_bf16_f32 v9, v10, v11
	v_add_u32_e32 v16, 0xb0, v170
	v_mad_i64_i32 v[16:17], s[34:35], v16, s82, v[142:143]
	v_lshl_add_u64 v[16:17], v[16:17], 0, v[140:141]
	global_store_dwordx2 v[16:17], v[8:9], off
	s_and_b64 vcc, exec, s[2:3]
	s_mov_b32 s86, s83
	s_mov_b32 s85, s84
	s_mov_b64 s[36:37], s[0:1]
	s_mov_b64 s[34:35], s[4:5]

; #define PG8_STAGE(bufoff, gbase, voff) do { _Pragma("unroll") for (int _i = 0; _i < 2; ++_i) \
;         __builtin_amdgcn_global_load_lds((const unsigned*)((const char*)(gbase) + (voff)[_i]), (PG8_LAS unsigned*)(lds + (bufoff) + ldsw + _i * 8192), 16, 0, 0); } while (0)
; #define PG8_LDA(dst, b, h) do { _Pragma("unroll") for (int m = 0; m < 4; ++m) _Pragma("unroll") for (int k = 0; k < 2; ++k) dst[m][k] = *(const PG8_LAS bf16x8*)(lds + PG8_SA(b, h) + aoff + m * 2048 + k * 1024); } while (0)
; #define PG8_LDB(dst, b, h) do { _Pragma("unroll") for (int n = 0; n < 2; ++n) _Pragma("unroll") for (int k = 0; k < 2; ++k) dst[n][k] = *(const PG8_LAS bf16x8*)(lds + PG8_SB(b, h) + boff + n * 2048 + k * 1024); } while (0)
; #define PG8_WAIT_V(n) asm volatile("s_waitcnt vmcnt(" #n ")" ::: "memory")
; #define PG8_WAIT_L(n) asm volatile("s_waitcnt lgkmcnt(" #n ")" ::: "memory")
; #define PG8_BAR __builtin_amdgcn_s_barrier()
; #define PG8_SCHED __builtin_amdgcn_sched_barrier(0)
; template <class Epi, class Sched, bool STAMP = false>
; __device__ __forceinline__ void gemm_phase(PG8_LAS unsigned char* lds, const Gemm g, const Sched& S, const Epi& E, unsigned long long* stamps) {
;     ...
;         for (int t = 0; t < nt; t += 2) {
;             const bool last = (t == nt - 2);
;             const char* a1 = cA + (size_t)(t + 1) * kstep;
;             const char* a2 = last ? nA : cA + (size_t)(t + 2) * kstep; const char* b2 = last ? nB : cB + (size_t)(t + 2) * kstep;
;             const char* a3 = a2 + kstep; const char* b3 = b2 + kstep;
;             if (last && has_next) S.a_ready(nxt);
;             PG8_LDB(B0, 0, 0); PG8_SCHED; PG8_LDA(At, 0, 0); PG8_STAGE(PG8_SA(1, 1), a1 + hstep, voffA);
;             PG8_WAIT_L(8); PG8_BAR; PG8_WAIT_L(0); PG8_MMA(0, 0, At, B0); PG8_BAR; PG8_SCHED;
;             PG8_LDB(B1, 0, 1); PG8_STAGE(PG8_SB(0, 0), b2, voffB);
;             PG8_BAR; PG8_WAIT_L(0); PG8_MMA(0, 1, At, B1); PG8_BAR;
;             PG8_LDA(At, 0, 1); PG8_STAGE(PG8_SA(0, 0), a2, voffA);
;             PG8_BAR; PG8_WAIT_L(0); PG8_MMA(1, 0, At, B0); PG8_BAR; PG8_SCHED;
;             PG8_STAGE(PG8_SB(0, 1), b2 + hstep, voffB);
;             PG8_WAIT_V(6); PG8_BAR; PG8_MMA(1, 1, At, B1); PG8_BAR;
;             PG8_LDB(B0, 1, 0); PG8_SCHED; PG8_LDA(At, 1, 0); PG8_STAGE(PG8_SA(0, 1), a2 + hstep, voffA);
.Lgu3_half_loop:
	ds_read_b128 v[140:143], v147
	ds_read_b128 v[170:173], v148
	ds_read_b128 v[174:177], v149
	ds_read_b128 v[178:181], v150
	s_add_u32 s36, s34, 0x100
	s_addc_u32 s37, s35, 0
	s_cmp_eq_u32 s10, 12
	s_cselect_b32 s43, s5, s37
	s_cselect_b32 s42, s4, s36
	s_cselect_b32 s41, s1, s78
	s_cselect_b32 s40, s0, s77
	s_mov_b32 m0, s67
	v_lshl_add_u64 v[214:215], s[34:35], 0, v[132:133]
	ds_read_b128 v[182:185], v145
	ds_read_b128 v[186:189], v145 offset:1024
	ds_read_b128 v[190:193], v145 offset:2048
	ds_read_b128 v[194:197], v145 offset:3072
	ds_read_b128 v[198:201], v145 offset:4096
	ds_read_b128 v[202:205], v145 offset:5120
	ds_read_b128 v[206:209], v145 offset:6144
	ds_read_b128 v[210:213], v145 offset:7168
	global_load_lds_dwordx4 v[214:215], off
	v_lshl_add_u64 v[214:215], s[34:35], 0, v[134:135]
	s_mov_b32 m0, s68
	s_nop 0
	global_load_lds_dwordx4 v[214:215], off
	s_waitcnt lgkmcnt(8)
	s_barrier
	s_waitcnt lgkmcnt(0)
	s_setprio 1
	s_waitcnt lgkmcnt(0)
	v_mfma_f32_16x16x32_bf16 v[124:127], v[140:143], v[182:185], v[124:127]
	v_mfma_f32_16x16x32_bf16 v[120:123], v[174:177], v[182:185], v[120:123]
	v_mfma_f32_16x16x32_bf16 v[108:111], v[140:143], v[190:193], v[108:111]
	v_mfma_f32_16x16x32_bf16 v[104:107], v[174:177], v[190:193], v[104:107]
	v_mfma_f32_16x16x32_bf16 v[92:95], v[140:143], v[198:201], v[92:95]
	v_mfma_f32_16x16x32_bf16 v[88:91], v[174:177], v[198:201], v[88:91]
	v_mfma_f32_16x16x32_bf16 v[76:79], v[140:143], v[206:209], v[76:79]
	v_mfma_f32_16x16x32_bf16 v[72:75], v[174:177], v[206:209], v[72:75]
	v_mfma_f32_16x16x32_bf16 v[124:127], v[170:173], v[186:189], v[124:127]
	v_mfma_f32_16x16x32_bf16 v[120:123], v[178:181], v[186:189], v[120:123]
	v_mfma_f32_16x16x32_bf16 v[108:111], v[170:173], v[194:197], v[108:111]
	v_mfma_f32_16x16x32_bf16 v[104:107], v[178:181], v[194:197], v[104:107]
	v_mfma_f32_16x16x32_bf16 v[92:95], v[170:173], v[202:205], v[92:95]
	v_mfma_f32_16x16x32_bf16 v[88:91], v[178:181], v[202:205], v[88:91]
	v_mfma_f32_16x16x32_bf16 v[76:79], v[170:173], v[210:213], v[76:79]
	v_mfma_f32_16x16x32_bf16 v[72:75], v[178:181], v[210:213], v[72:75]
	s_setprio 0
	s_barrier
	s_mov_b32 m0, s49
	v_lshl_add_u64 v[230:231], s[40:41], 0, v[130:131]
	global_load_lds_dwordx4 v[230:231], off
	v_lshl_add_u64 v[232:233], s[40:41], 0, v[128:129]
	s_mov_b32 m0, s52
	s_nop 0
	global_load_lds_dwordx4 v[232:233], off
	s_barrier
	s_waitcnt lgkmcnt(0)
	s_setprio 1
	s_waitcnt lgkmcnt(0)
	s_setprio 0
	s_mov_b32 m0, s46
	v_lshl_add_u64 v[234:235], s[42:43], 0, v[130:131]
	s_barrier
	ds_read_b128 v[182:185], v145 offset:16384
	ds_read_b128 v[186:189], v145 offset:17408
	ds_read_b128 v[190:193], v145 offset:18432
	ds_read_b128 v[194:197], v145 offset:19456
	ds_read_b128 v[198:201], v145 offset:20480
	ds_read_b128 v[202:205], v145 offset:21504
	ds_read_b128 v[206:209], v145 offset:22528
	ds_read_b128 v[210:213], v145 offset:23552
	global_load_lds_dwordx4 v[234:235], off
	v_lshl_add_u64 v[236:237], s[42:43], 0, v[128:129]
	s_mov_b32 m0, s53
	s_nop 0
	global_load_lds_dwordx4 v[236:237], off
	s_barrier
	s_waitcnt lgkmcnt(0)
	s_setprio 1
	s_waitcnt lgkmcnt(0)
	v_mfma_f32_16x16x32_bf16 v[60:63], v[140:143], v[182:185], v[60:63]
	v_mfma_f32_16x16x32_bf16 v[56:59], v[174:177], v[182:185], v[56:59]
	v_mfma_f32_16x16x32_bf16 v[44:47], v[140:143], v[190:193], v[44:47]
	v_mfma_f32_16x16x32_bf16 v[40:43], v[174:177], v[190:193], v[40:43]
	v_mfma_f32_16x16x32_bf16 v[28:31], v[140:143], v[198:201], v[28:31]
	v_mfma_f32_16x16x32_bf16 v[24:27], v[174:177], v[198:201], v[24:27]
	v_mfma_f32_16x16x32_bf16 v[12:15], v[140:143], v[206:209], v[12:15]
	v_mfma_f32_16x16x32_bf16 v[8:11], v[174:177], v[206:209], v[8:11]
	v_mfma_f32_16x16x32_bf16 v[60:63], v[170:173], v[186:189], v[60:63]
	v_mfma_f32_16x16x32_bf16 v[56:59], v[178:181], v[186:189], v[56:59]
	v_mfma_f32_16x16x32_bf16 v[44:47], v[170:173], v[194:197], v[44:47]
	v_mfma_f32_16x16x32_bf16 v[40:43], v[178:181], v[194:197], v[40:43]
	v_mfma_f32_16x16x32_bf16 v[28:31], v[170:173], v[202:205], v[28:31]
	v_mfma_f32_16x16x32_bf16 v[24:27], v[178:181], v[202:205], v[24:27]
	v_mfma_f32_16x16x32_bf16 v[12:15], v[170:173], v[210:213], v[12:15]
	v_mfma_f32_16x16x32_bf16 v[8:11], v[178:181], v[210:213], v[8:11]
	s_setprio 0
	s_barrier
	s_add_u32 s34, s40, 0x44000
	s_addc_u32 s35, s41, 0
	s_mov_b32 m0, s54
	v_lshl_add_u64 v[140:141], s[34:35], 0, v[130:131]
	global_load_lds_dwordx4 v[140:141], off
	v_lshl_add_u64 v[140:141], s[34:35], 0, v[128:129]
	s_mov_b32 m0, s55
	s_nop 0
	global_load_lds_dwordx4 v[140:141], off
	s_waitcnt vmcnt(6)
	s_barrier
	s_setprio 1
	s_setprio 0
	s_barrier
	ds_read_b128 v[140:143], v155
	ds_read_b128 v[170:173], v156
	ds_read_b128 v[174:177], v157
	ds_read_b128 v[178:181], v165
	s_add_u32 s34, s42, 0x44000
	s_addc_u32 s35, s43, 0
	s_mov_b32 m0, s56
	v_lshl_add_u64 v[214:215], s[34:35], 0, v[130:131]
	ds_read_b128 v[182:185], v145 offset:32768
	ds_read_b128 v[186:189], v145 offset:33792
	ds_read_b128 v[190:193], v145 offset:34816
	ds_read_b128 v[194:197], v145 offset:35840
	ds_read_b128 v[198:201], v145 offset:36864
	ds_read_b128 v[202:205], v145 offset:37888
	ds_read_b128 v[206:209], v145 offset:38912
	ds_read_b128 v[210:213], v145 offset:39936
	global_load_lds_dwordx4 v[214:215], off
	v_lshl_add_u64 v[214:215], s[34:35], 0, v[128:129]
	s_mov_b32 m0, s57
	s_nop 0
	global_load_lds_dwordx4 v[214:215], off
	s_waitcnt lgkmcnt(8)
	s_barrier
; DI float ex2(float x) { return __builtin_amdgcn_exp2f(x); }
; #define PG8_STAGE(bufoff, gbase, voff) do { _Pragma("unroll") for (int _i = 0; _i < 2; ++_i) \
;         __builtin_amdgcn_global_load_lds((const unsigned*)((const char*)(gbase) + (voff)[_i]), (PG8_LAS unsigned*)(lds + (bufoff) + ldsw + _i * 8192), 16, 0, 0); } while (0)
; #define PG8_LDA(dst, b, h) do { _Pragma("unroll") for (int m = 0; m < 4; ++m) _Pragma("unroll") for (int k = 0; k < 2; ++k) dst[m][k] = *(const PG8_LAS bf16x8*)(lds + PG8_SA(b, h) + aoff + m * 2048 + k * 1024); } while (0)
; #define PG8_WAIT_V(n) asm volatile("s_waitcnt vmcnt(" #n ")" ::: "memory")
; #define PG8_WAIT_L(n) asm volatile("s_waitcnt lgkmcnt(" #n ")" ::: "memory")
; #define PG8_BAR __builtin_amdgcn_s_barrier()
;     DI void operator()(const f32x4 (&acc)[2][2][4][2], const Unit& u, int wr, int wc, int fr, int fq) const {
;         const int row0 = u.pm * BM + wr * 64 + fr, hcol0 = ((u.pn * BM + wc * 32) >> 1) + 4 * fq;
; #pragma unroll
;         for (int ai = 0; ai < 2; ++ai)
; #pragma unroll
;             for (int m = 0; m < 4; ++m) { u16* rowp = O + (size_t)(row0 + ai * HALF + m * 16) * ldc + hcol0;
; #pragma unroll
;                 for (int bj = 0; bj < 2; ++bj) { const f32x4 g = acc[ai][bj][m][0], up = acc[ai][bj][m][1]; float r[4];
; #pragma unroll
;                     for (int j = 0; j < 4; ++j) r[j] = g[j] * up[j] * __builtin_amdgcn_rcpf(1.f + ex2(-LOG2E * g[j]));
;                     uint2 w = {pack2(r[0], r[1]), pack2(r[2], r[3])}; *(uint2*)(rowp + bj * (HALF / 2)) = w; } }
; template <class Epi, class Sched, bool STAMP = false>
; __device__ __forceinline__ void gemm_phase(PG8_LAS unsigned char* lds, const Gemm g, const Sched& S, const Epi& E, unsigned long long* stamps) {
;     ...
;             PG8_LDB(B0, 1, 0); PG8_SCHED; PG8_LDA(At, 1, 0); PG8_STAGE(PG8_SA(0, 1), a2 + hstep, voffA);
;             PG8_WAIT_L(8); PG8_BAR; PG8_WAIT_L(0); PG8_MMA(0, 0, At, B0); PG8_BAR; PG8_SCHED;
;             PG8_LDB(B1, 1, 1); PG8_STAGE(PG8_SB(1, 0), b3, voffB);
;             PG8_BAR; PG8_WAIT_L(0); PG8_MMA(0, 1, At, B1); PG8_BAR;
;             PG8_LDA(At, 1, 1); PG8_STAGE(PG8_SA(1, 0), a3, voffA);
;             PG8_BAR; PG8_WAIT_L(0); PG8_MMA(1, 0, At, B0); PG8_BAR; PG8_SCHED;
;             PG8_STAGE(PG8_SB(1, 1), b3 + hstep, voffB);
;             PG8_WAIT_V(6); PG8_BAR; PG8_MMA(1, 1, At, B1); PG8_BAR;
;         }
	s_waitcnt lgkmcnt(0)
	s_setprio 1
	s_waitcnt lgkmcnt(0)
	v_mfma_f32_16x16x32_bf16 v[124:127], v[140:143], v[182:185], v[124:127]
	v_mfma_f32_16x16x32_bf16 v[120:123], v[174:177], v[182:185], v[120:123]
	v_mfma_f32_16x16x32_bf16 v[108:111], v[140:143], v[190:193], v[108:111]
	v_mfma_f32_16x16x32_bf16 v[104:107], v[174:177], v[190:193], v[104:107]
	v_mfma_f32_16x16x32_bf16 v[92:95], v[140:143], v[198:201], v[92:95]
	v_mfma_f32_16x16x32_bf16 v[88:91], v[174:177], v[198:201], v[88:91]
	v_mfma_f32_16x16x32_bf16 v[76:79], v[140:143], v[206:209], v[76:79]
	v_mfma_f32_16x16x32_bf16 v[72:75], v[174:177], v[206:209], v[72:75]
	v_mfma_f32_16x16x32_bf16 v[124:127], v[170:173], v[186:189], v[124:127]
	v_mfma_f32_16x16x32_bf16 v[120:123], v[178:181], v[186:189], v[120:123]
	v_mfma_f32_16x16x32_bf16 v[108:111], v[170:173], v[194:197], v[108:111]
	v_mfma_f32_16x16x32_bf16 v[104:107], v[178:181], v[194:197], v[104:107]
	v_mfma_f32_16x16x32_bf16 v[92:95], v[170:173], v[202:205], v[92:95]
	v_mfma_f32_16x16x32_bf16 v[88:91], v[178:181], v[202:205], v[88:91]
	v_mfma_f32_16x16x32_bf16 v[76:79], v[170:173], v[210:213], v[76:79]
	v_mfma_f32_16x16x32_bf16 v[72:75], v[178:181], v[210:213], v[72:75]
	s_setprio 0
	s_barrier
	s_mov_b32 m0, s60
	v_lshl_add_u64 v[230:231], v[230:231], 0, s[6:7]
	global_load_lds_dwordx4 v[230:231], off
	v_lshl_add_u64 v[230:231], v[232:233], 0, s[6:7]
	s_mov_b32 m0, s61
	s_nop 0
	global_load_lds_dwordx4 v[230:231], off
	s_barrier
	s_waitcnt lgkmcnt(0)
	s_setprio 1
	s_waitcnt lgkmcnt(0)
	s_setprio 0
	s_mov_b32 m0, s62
	v_lshl_add_u64 v[230:231], v[234:235], 0, s[6:7]
	s_barrier
	ds_read_b128 v[182:185], v145 offset:49152
	ds_read_b128 v[186:189], v145 offset:50176
	ds_read_b128 v[190:193], v145 offset:51200
	ds_read_b128 v[194:197], v145 offset:52224
	ds_read_b128 v[198:201], v145 offset:53248
	ds_read_b128 v[202:205], v145 offset:54272
	ds_read_b128 v[206:209], v145 offset:55296
	ds_read_b128 v[210:213], v145 offset:56320
	global_load_lds_dwordx4 v[230:231], off
	v_lshl_add_u64 v[230:231], v[236:237], 0, s[6:7]
	s_mov_b32 m0, s63
	s_nop 0
	global_load_lds_dwordx4 v[230:231], off
	s_barrier
	s_waitcnt lgkmcnt(0)
	s_setprio 1
	s_waitcnt lgkmcnt(0)
	v_mfma_f32_16x16x32_bf16 v[60:63], v[140:143], v[182:185], v[60:63]
	v_mfma_f32_16x16x32_bf16 v[56:59], v[174:177], v[182:185], v[56:59]
	v_mfma_f32_16x16x32_bf16 v[44:47], v[140:143], v[190:193], v[44:47]
	v_mfma_f32_16x16x32_bf16 v[40:43], v[174:177], v[190:193], v[40:43]
	v_mfma_f32_16x16x32_bf16 v[28:31], v[140:143], v[198:201], v[28:31]
	v_mfma_f32_16x16x32_bf16 v[24:27], v[174:177], v[198:201], v[24:27]
	v_mfma_f32_16x16x32_bf16 v[12:15], v[140:143], v[206:209], v[12:15]
	v_mfma_f32_16x16x32_bf16 v[8:11], v[174:177], v[206:209], v[8:11]
	v_mfma_f32_16x16x32_bf16 v[60:63], v[170:173], v[186:189], v[60:63]
	v_mfma_f32_16x16x32_bf16 v[56:59], v[178:181], v[186:189], v[56:59]
	v_mfma_f32_16x16x32_bf16 v[44:47], v[170:173], v[194:197], v[44:47]
	v_mfma_f32_16x16x32_bf16 v[40:43], v[178:181], v[194:197], v[40:43]
	v_mfma_f32_16x16x32_bf16 v[28:31], v[170:173], v[202:205], v[28:31]
	v_mfma_f32_16x16x32_bf16 v[24:27], v[178:181], v[202:205], v[24:27]
	v_mfma_f32_16x16x32_bf16 v[12:15], v[170:173], v[210:213], v[12:15]
	v_mfma_f32_16x16x32_bf16 v[8:11], v[178:181], v[210:213], v[8:11]
	s_setprio 0
	s_barrier
	s_add_u32 s34, s40, 0x44080
	s_addc_u32 s35, s41, 0
	s_mov_b32 m0, s64
	v_lshl_add_u64 v[140:141], s[34:35], 0, v[130:131]
	global_load_lds_dwordx4 v[140:141], off
	v_lshl_add_u64 v[140:141], s[34:35], 0, v[128:129]
	s_mov_b32 m0, s65
	s_nop 0
	global_load_lds_dwordx4 v[140:141], off
	s_waitcnt vmcnt(6)
	s_barrier
	s_setprio 1
	s_setprio 0
	s_add_i32 s10, s10, 2
	s_add_u32 s77, s77, 0x100
	s_addc_u32 s78, s78, 0
	s_cmp_gt_u32 s10, 13
	s_mov_b64 s[34:35], s[36:37]
	s_barrier
	s_cbranch_scc0 .Lgu3_half_loop
	v_mul_f32_e32 v171, 0xbfb8aa3b, v124
	v_exp_f32_e32 v171, v171
	v_mul_f32_e32 v174, 0xbfb8aa3b, v125
	v_exp_f32_e32 v175, v174
	s_lshl_b32 s10, s76, 8
	v_add_f32_e32 v171, 1.0, v171
	v_rcp_f32_e32 v174, v171
	v_add_f32_e32 v171, 1.0, v175
	v_mul_f32_e32 v175, 0xbfb8aa3b, v126
	v_exp_f32_e32 v176, v175
	v_mul_f32_e32 v175, 0xbfb8aa3b, v127
	v_exp_f32_e32 v177, v175
	v_rcp_f32_e32 v175, v171
	v_add_f32_e32 v171, 1.0, v176
	v_rcp_f32_e32 v176, v171
	v_add_f32_e32 v171, 1.0, v177
	v_rcp_f32_e32 v177, v171
	v_pk_mul_f32 v[122:123], v[126:127], v[122:123]
	v_pk_mul_f32 v[120:121], v[124:125], v[120:121]
	s_or_b32 s10, s10, s59
	s_or_b32 s10, s10, s98
	v_pk_mul_f32 v[120:121], v[120:121], v[174:175]
	v_pk_mul_f32 v[122:123], v[122:123], v[176:177]
	s_ashr_i32 s10, s10, 1
	v_cvt_pk_bf16_f32 v120, v120, v121
	v_cvt_pk_bf16_f32 v121, v122, v123
	v_or_b32_e32 v140, s10, v146
	v_lshl_add_u32 v170, s75, 8, v144
	v_ashrrev_i32_e32 v141, 31, v140
	v_mov_b64_e32 v[142:143], s[12:13]
	v_mad_i64_i32 v[172:173], s[34:35], v170, s69, v[142:143]
	v_lshlrev_b64 v[140:141], 1, v[140:141]
	v_lshl_add_u64 v[172:173], v[172:173], 0, v[140:141]
	global_store_dwordx2 v[172:173], v[120:121], off
	v_mul_f32_e32 v116, 0xbfb8aa3b, v110
	v_mul_f32_e32 v114, 0xbfb8aa3b, v108
	v_mul_f32_e32 v115, 0xbfb8aa3b, v109
	v_mul_f32_e32 v117, 0xbfb8aa3b, v111
	v_exp_f32_e32 v114, v114
	v_exp_f32_e32 v115, v115
	v_exp_f32_e32 v116, v116
	v_exp_f32_e32 v117, v117
	v_add_f32_e32 v114, 1.0, v114
	v_add_f32_e32 v115, 1.0, v115
	v_add_f32_e32 v116, 1.0, v116
	v_add_f32_e32 v117, 1.0, v117
	v_rcp_f32_e32 v114, v114
	v_rcp_f32_e32 v115, v115
	v_rcp_f32_e32 v116, v116
	v_rcp_f32_e32 v117, v117
	v_pk_mul_f32 v[106:107], v[110:111], v[106:107]
	v_pk_mul_f32 v[104:105], v[108:109], v[104:105]
	v_pk_mul_f32 v[104:105], v[104:105], v[114:115]
; DI float ex2(float x) { return __builtin_amdgcn_exp2f(x); }
;     DI void operator()(const f32x4 (&acc)[2][2][4][2], const Unit& u, int wr, int wc, int fr, int fq) const {
;         const int row0 = u.pm * BM + wr * 64 + fr, hcol0 = ((u.pn * BM + wc * 32) >> 1) + 4 * fq;
; #pragma unroll
;         for (int ai = 0; ai < 2; ++ai)
; #pragma unroll
;             for (int m = 0; m < 4; ++m) { u16* rowp = O + (size_t)(row0 + ai * HALF + m * 16) * ldc + hcol0;
; #pragma unroll
;                 for (int bj = 0; bj < 2; ++bj) { const f32x4 g = acc[ai][bj][m][0], up = acc[ai][bj][m][1]; float r[4];
; #pragma unroll
;                     for (int j = 0; j < 4; ++j) r[j] = g[j] * up[j] * __builtin_amdgcn_rcpf(1.f + ex2(-LOG2E * g[j]));
;                     uint2 w = {pack2(r[0], r[1]), pack2(r[2], r[3])}; *(uint2*)(rowp + bj * (HALF / 2)) = w; } }
	v_pk_mul_f32 v[106:107], v[106:107], v[116:117]
	v_cvt_pk_bf16_f32 v104, v104, v105
	v_cvt_pk_bf16_f32 v105, v106, v107
	v_or_b32_e32 v112, 16, v170
	v_mad_i64_i32 v[112:113], s[34:35], v112, s69, v[142:143]
	v_lshl_add_u64 v[112:113], v[112:113], 0, v[140:141]
	global_store_dwordx2 v[112:113], v[104:105], off
	v_mul_f32_e32 v100, 0xbfb8aa3b, v94
	v_mul_f32_e32 v98, 0xbfb8aa3b, v92
	v_mul_f32_e32 v99, 0xbfb8aa3b, v93
	v_mul_f32_e32 v101, 0xbfb8aa3b, v95
	v_exp_f32_e32 v98, v98
	v_exp_f32_e32 v99, v99
	v_exp_f32_e32 v100, v100
	v_exp_f32_e32 v101, v101
	v_add_f32_e32 v98, 1.0, v98
	v_add_f32_e32 v99, 1.0, v99
	v_add_f32_e32 v100, 1.0, v100
	v_add_f32_e32 v101, 1.0, v101
	v_rcp_f32_e32 v98, v98
	v_rcp_f32_e32 v99, v99
	v_rcp_f32_e32 v100, v100
	v_rcp_f32_e32 v101, v101
	v_pk_mul_f32 v[90:91], v[94:95], v[90:91]
	v_pk_mul_f32 v[88:89], v[92:93], v[88:89]
	v_pk_mul_f32 v[88:89], v[88:89], v[98:99]
	v_pk_mul_f32 v[90:91], v[90:91], v[100:101]
	v_cvt_pk_bf16_f32 v88, v88, v89
	v_cvt_pk_bf16_f32 v89, v90, v91
	v_or_b32_e32 v96, 32, v170
	v_mad_i64_i32 v[96:97], s[34:35], v96, s69, v[142:143]
	v_lshl_add_u64 v[96:97], v[96:97], 0, v[140:141]
	global_store_dwordx2 v[96:97], v[88:89], off
	v_mul_f32_e32 v84, 0xbfb8aa3b, v78
	v_mul_f32_e32 v82, 0xbfb8aa3b, v76
	v_mul_f32_e32 v83, 0xbfb8aa3b, v77
	v_mul_f32_e32 v85, 0xbfb8aa3b, v79
	v_exp_f32_e32 v82, v82
	v_exp_f32_e32 v83, v83
	v_exp_f32_e32 v84, v84
	v_exp_f32_e32 v85, v85
	v_add_f32_e32 v82, 1.0, v82
	v_add_f32_e32 v83, 1.0, v83
	v_add_f32_e32 v84, 1.0, v84
	v_add_f32_e32 v85, 1.0, v85
	v_rcp_f32_e32 v82, v82
	v_rcp_f32_e32 v83, v83
	v_rcp_f32_e32 v84, v84
	v_rcp_f32_e32 v85, v85
	v_pk_mul_f32 v[74:75], v[78:79], v[74:75]
	v_pk_mul_f32 v[72:73], v[76:77], v[72:73]
	v_pk_mul_f32 v[72:73], v[72:73], v[82:83]
	v_pk_mul_f32 v[74:75], v[74:75], v[84:85]
	v_cvt_pk_bf16_f32 v72, v72, v73
	v_cvt_pk_bf16_f32 v73, v74, v75
	v_or_b32_e32 v80, 48, v170
	v_mad_i64_i32 v[80:81], s[34:35], v80, s69, v[142:143]
	v_lshl_add_u64 v[80:81], v[80:81], 0, v[140:141]
	global_store_dwordx2 v[80:81], v[72:73], off
	v_mul_f32_e32 v68, 0xbfb8aa3b, v62
	v_mul_f32_e32 v66, 0xbfb8aa3b, v60
	v_mul_f32_e32 v67, 0xbfb8aa3b, v61
	v_mul_f32_e32 v69, 0xbfb8aa3b, v63
	v_exp_f32_e32 v66, v66
	v_exp_f32_e32 v67, v67
	v_exp_f32_e32 v68, v68
	v_exp_f32_e32 v69, v69
	v_add_f32_e32 v66, 1.0, v66
	v_add_f32_e32 v67, 1.0, v67
	v_add_f32_e32 v68, 1.0, v68
	v_add_f32_e32 v69, 1.0, v69
	v_rcp_f32_e32 v66, v66
	v_rcp_f32_e32 v67, v67
	v_rcp_f32_e32 v68, v68
	v_rcp_f32_e32 v69, v69
	v_pk_mul_f32 v[58:59], v[62:63], v[58:59]
	v_pk_mul_f32 v[56:57], v[60:61], v[56:57]
	v_pk_mul_f32 v[56:57], v[56:57], v[66:67]
	v_pk_mul_f32 v[58:59], v[58:59], v[68:69]
	v_cvt_pk_bf16_f32 v56, v56, v57
	v_cvt_pk_bf16_f32 v57, v58, v59
	v_add_u32_e32 v64, 0x80, v170
	v_mad_i64_i32 v[64:65], s[34:35], v64, s69, v[142:143]
	v_lshl_add_u64 v[64:65], v[64:65], 0, v[140:141]
	global_store_dwordx2 v[64:65], v[56:57], off
	v_mul_f32_e32 v52, 0xbfb8aa3b, v46
	v_mul_f32_e32 v50, 0xbfb8aa3b, v44
	v_mul_f32_e32 v51, 0xbfb8aa3b, v45
	v_mul_f32_e32 v53, 0xbfb8aa3b, v47
	v_exp_f32_e32 v50, v50
	v_exp_f32_e32 v51, v51
	v_exp_f32_e32 v52, v52
	v_exp_f32_e32 v53, v53
	v_add_f32_e32 v50, 1.0, v50
	v_add_f32_e32 v51, 1.0, v51
	v_add_f32_e32 v52, 1.0, v52
	v_add_f32_e32 v53, 1.0, v53
	v_rcp_f32_e32 v50, v50
	v_rcp_f32_e32 v51, v51
	v_rcp_f32_e32 v52, v52
	v_rcp_f32_e32 v53, v53
	v_pk_mul_f32 v[42:43], v[46:47], v[42:43]
	v_pk_mul_f32 v[40:41], v[44:45], v[40:41]
	v_pk_mul_f32 v[40:41], v[40:41], v[50:51]
	v_pk_mul_f32 v[42:43], v[42:43], v[52:53]
	v_cvt_pk_bf16_f32 v40, v40, v41
	v_cvt_pk_bf16_f32 v41, v42, v43
	v_add_u32_e32 v48, 0x90, v170
	v_mad_i64_i32 v[48:49], s[34:35], v48, s69, v[142:143]
	v_lshl_add_u64 v[48:49], v[48:49], 0, v[140:141]
	global_store_dwordx2 v[48:49], v[40:41], off
	v_mul_f32_e32 v36, 0xbfb8aa3b, v30
	v_mul_f32_e32 v34, 0xbfb8aa3b, v28
	v_mul_f32_e32 v35, 0xbfb8aa3b, v29
	v_mul_f32_e32 v37, 0xbfb8aa3b, v31
	v_exp_f32_e32 v34, v34
	v_exp_f32_e32 v35, v35
	v_exp_f32_e32 v36, v36
	v_exp_f32_e32 v37, v37
	v_add_f32_e32 v34, 1.0, v34
	v_add_f32_e32 v35, 1.0, v35
	v_add_f32_e32 v36, 1.0, v36
	v_add_f32_e32 v37, 1.0, v37
	v_rcp_f32_e32 v34, v34
	v_rcp_f32_e32 v35, v35
	v_rcp_f32_e32 v36, v36
	v_rcp_f32_e32 v37, v37
	v_pk_mul_f32 v[26:27], v[30:31], v[26:27]
	v_pk_mul_f32 v[24:25], v[28:29], v[24:25]
	v_pk_mul_f32 v[24:25], v[24:25], v[34:35]
	v_pk_mul_f32 v[26:27], v[26:27], v[36:37]
	v_cvt_pk_bf16_f32 v24, v24, v25
	v_cvt_pk_bf16_f32 v25, v26, v27
	v_add_u32_e32 v32, 0xa0, v170
	v_mad_i64_i32 v[32:33], s[34:35], v32, s69, v[142:143]
	v_lshl_add_u64 v[32:33], v[32:33], 0, v[140:141]
	global_store_dwordx2 v[32:33], v[24:25], off
	v_mul_f32_e32 v20, 0xbfb8aa3b, v14
	v_mul_f32_e32 v18, 0xbfb8aa3b, v12
	v_mul_f32_e32 v19, 0xbfb8aa3b, v13
	v_mul_f32_e32 v21, 0xbfb8aa3b, v15
	v_exp_f32_e32 v18, v18
	v_exp_f32_e32 v19, v19
	v_exp_f32_e32 v20, v20
	v_exp_f32_e32 v21, v21
	v_add_f32_e32 v18, 1.0, v18
	v_add_f32_e32 v19, 1.0, v19
	v_add_f32_e32 v20, 1.0, v20
	v_add_f32_e32 v21, 1.0, v21
	v_rcp_f32_e32 v18, v18
	v_rcp_f32_e32 v19, v19
	v_rcp_f32_e32 v20, v20
	v_rcp_f32_e32 v21, v21
	v_pk_mul_f32 v[10:11], v[14:15], v[10:11]
	v_pk_mul_f32 v[8:9], v[12:13], v[8:9]
	v_pk_mul_f32 v[8:9], v[8:9], v[18:19]
	v_pk_mul_f32 v[10:11], v[10:11], v[20:21]
	v_cvt_pk_bf16_f32 v8, v8, v9
	v_cvt_pk_bf16_f32 v9, v10, v11
	v_add_u32_e32 v16, 0xb0, v170
	v_mad_i64_i32 v[16:17], s[34:35], v16, s69, v[142:143]
	v_lshl_add_u64 v[16:17], v[16:17], 0, v[140:141]
	global_store_dwordx2 v[16:17], v[8:9], off
	s_and_b64 vcc, exec, s[2:3]
	s_mov_b32 s76, s70
	s_mov_b32 s75, s71
	s_mov_b64 s[36:37], s[0:1]
	s_mov_b64 s[34:35], s[4:5]

; #define PG8_STAGE(bufoff, gbase, voff) do { _Pragma("unroll") for (int _i = 0; _i < 2; ++_i) \
;         __builtin_amdgcn_global_load_lds((const unsigned*)((const char*)(gbase) + (voff)[_i]), (PG8_LAS unsigned*)(lds + (bufoff) + ldsw + _i * 8192), 16, 0, 0); } while (0)
; #define PG8_LDA(dst, b, h) do { _Pragma("unroll") for (int m = 0; m < 4; ++m) _Pragma("unroll") for (int k = 0; k < 2; ++k) dst[m][k] = *(const PG8_LAS bf16x8*)(lds + PG8_SA(b, h) + aoff + m * 2048 + k * 1024); } while (0)
; #define PG8_LDB(dst, b, h) do { _Pragma("unroll") for (int n = 0; n < 2; ++n) _Pragma("unroll") for (int k = 0; k < 2; ++k) dst[n][k] = *(const PG8_LAS bf16x8*)(lds + PG8_SB(b, h) + boff + n * 2048 + k * 1024); } while (0)
; #define PG8_WAIT_V(n) asm volatile("s_waitcnt vmcnt(" #n ")" ::: "memory")
; #define PG8_WAIT_L(n) asm volatile("s_waitcnt lgkmcnt(" #n ")" ::: "memory")
; #define PG8_BAR __builtin_amdgcn_s_barrier()
; #define PG8_SCHED __builtin_amdgcn_sched_barrier(0)
; template <class Epi, class Sched, bool STAMP = false>
; __device__ __forceinline__ void gemm_phase(PG8_LAS unsigned char* lds, const Gemm g, const Sched& S, const Epi& E, unsigned long long* stamps) {
;     ...
;         for (int t = 0; t < nt; t += 2) {
;             const bool last = (t == nt - 2);
;             const char* a1 = cA + (size_t)(t + 1) * kstep;
;             const char* a2 = last ? nA : cA + (size_t)(t + 2) * kstep; const char* b2 = last ? nB : cB + (size_t)(t + 2) * kstep;
;             const char* a3 = a2 + kstep; const char* b3 = b2 + kstep;
;             if (last && has_next) S.a_ready(nxt);
;             PG8_LDB(B0, 0, 0); PG8_SCHED; PG8_LDA(At, 0, 0); PG8_STAGE(PG8_SA(1, 1), a1 + hstep, voffA);
;             PG8_WAIT_L(8); PG8_BAR; PG8_WAIT_L(0); PG8_MMA(0, 0, At, B0); PG8_BAR; PG8_SCHED;
;             PG8_LDB(B1, 0, 1); PG8_STAGE(PG8_SB(0, 0), b2, voffB);
;             PG8_BAR; PG8_WAIT_L(0); PG8_MMA(0, 1, At, B1); PG8_BAR;
;             PG8_LDA(At, 0, 1); PG8_STAGE(PG8_SA(0, 0), a2, voffA);
;             PG8_BAR; PG8_WAIT_L(0); PG8_MMA(1, 0, At, B0); PG8_BAR; PG8_SCHED;
;             PG8_STAGE(PG8_SB(0, 1), b2 + hstep, voffB);
;             PG8_WAIT_V(6); PG8_BAR; PG8_MMA(1, 1, At, B1); PG8_BAR;
;             PG8_LDB(B0, 1, 0); PG8_SCHED; PG8_LDA(At, 1, 0); PG8_STAGE(PG8_SA(0, 1), a2 + hstep, voffA);
.Lgu4_half_loop:
	ds_read_b128 v[140:143], v147
	ds_read_b128 v[170:173], v148
	ds_read_b128 v[174:177], v149
	ds_read_b128 v[178:181], v150
	s_add_u32 s18, s16, 0x100
	s_addc_u32 s19, s17, 0
	s_cmp_eq_u32 s10, 12
	s_cselect_b32 s29, s5, s19
	s_cselect_b32 s28, s4, s18
	s_cselect_b32 s21, s1, s63
	s_cselect_b32 s20, s0, s62
	s_mov_b32 m0, s55
	v_lshl_add_u64 v[214:215], s[16:17], 0, v[132:133]
	ds_read_b128 v[182:185], v145
	ds_read_b128 v[186:189], v145 offset:1024
	ds_read_b128 v[190:193], v145 offset:2048
	ds_read_b128 v[194:197], v145 offset:3072
	ds_read_b128 v[198:201], v145 offset:4096
	ds_read_b128 v[202:205], v145 offset:5120
	ds_read_b128 v[206:209], v145 offset:6144
	ds_read_b128 v[210:213], v145 offset:7168
	global_load_lds_dwordx4 v[214:215], off
	v_lshl_add_u64 v[214:215], s[16:17], 0, v[134:135]
	s_mov_b32 m0, s56
	s_nop 0
	global_load_lds_dwordx4 v[214:215], off
	s_waitcnt lgkmcnt(8)
	s_barrier
	s_waitcnt lgkmcnt(0)
	s_setprio 1
	s_waitcnt lgkmcnt(0)
	v_mfma_f32_16x16x32_bf16 v[124:127], v[140:143], v[182:185], v[124:127]
	v_mfma_f32_16x16x32_bf16 v[120:123], v[174:177], v[182:185], v[120:123]
	v_mfma_f32_16x16x32_bf16 v[108:111], v[140:143], v[190:193], v[108:111]
	v_mfma_f32_16x16x32_bf16 v[104:107], v[174:177], v[190:193], v[104:107]
	v_mfma_f32_16x16x32_bf16 v[92:95], v[140:143], v[198:201], v[92:95]
	v_mfma_f32_16x16x32_bf16 v[88:91], v[174:177], v[198:201], v[88:91]
	v_mfma_f32_16x16x32_bf16 v[76:79], v[140:143], v[206:209], v[76:79]
	v_mfma_f32_16x16x32_bf16 v[72:75], v[174:177], v[206:209], v[72:75]
	v_mfma_f32_16x16x32_bf16 v[124:127], v[170:173], v[186:189], v[124:127]
	v_mfma_f32_16x16x32_bf16 v[120:123], v[178:181], v[186:189], v[120:123]
	v_mfma_f32_16x16x32_bf16 v[108:111], v[170:173], v[194:197], v[108:111]
	v_mfma_f32_16x16x32_bf16 v[104:107], v[178:181], v[194:197], v[104:107]
	v_mfma_f32_16x16x32_bf16 v[92:95], v[170:173], v[202:205], v[92:95]
	v_mfma_f32_16x16x32_bf16 v[88:91], v[178:181], v[202:205], v[88:91]
	v_mfma_f32_16x16x32_bf16 v[76:79], v[170:173], v[210:213], v[76:79]
	v_mfma_f32_16x16x32_bf16 v[72:75], v[178:181], v[210:213], v[72:75]
	s_setprio 0
	s_barrier
	s_mov_b32 m0, s37
	v_lshl_add_u64 v[230:231], s[20:21], 0, v[130:131]
	global_load_lds_dwordx4 v[230:231], off
	v_lshl_add_u64 v[232:233], s[20:21], 0, v[128:129]
	s_mov_b32 m0, s40
	s_nop 0
	global_load_lds_dwordx4 v[232:233], off
	s_barrier
	s_waitcnt lgkmcnt(0)
	s_setprio 1
	s_waitcnt lgkmcnt(0)
	s_setprio 0
	s_mov_b32 m0, s34
	v_lshl_add_u64 v[234:235], s[28:29], 0, v[130:131]
	s_barrier
	ds_read_b128 v[182:185], v145 offset:16384
	ds_read_b128 v[186:189], v145 offset:17408
	ds_read_b128 v[190:193], v145 offset:18432
	ds_read_b128 v[194:197], v145 offset:19456
	ds_read_b128 v[198:201], v145 offset:20480
	ds_read_b128 v[202:205], v145 offset:21504
	ds_read_b128 v[206:209], v145 offset:22528
	ds_read_b128 v[210:213], v145 offset:23552
	global_load_lds_dwordx4 v[234:235], off
	v_lshl_add_u64 v[236:237], s[28:29], 0, v[128:129]
	s_mov_b32 m0, s41
	s_nop 0
	global_load_lds_dwordx4 v[236:237], off
	s_barrier
	s_waitcnt lgkmcnt(0)
	s_setprio 1
	s_waitcnt lgkmcnt(0)
	v_mfma_f32_16x16x32_bf16 v[60:63], v[140:143], v[182:185], v[60:63]
	v_mfma_f32_16x16x32_bf16 v[56:59], v[174:177], v[182:185], v[56:59]
	v_mfma_f32_16x16x32_bf16 v[44:47], v[140:143], v[190:193], v[44:47]
	v_mfma_f32_16x16x32_bf16 v[40:43], v[174:177], v[190:193], v[40:43]
	v_mfma_f32_16x16x32_bf16 v[28:31], v[140:143], v[198:201], v[28:31]
	v_mfma_f32_16x16x32_bf16 v[24:27], v[174:177], v[198:201], v[24:27]
	v_mfma_f32_16x16x32_bf16 v[12:15], v[140:143], v[206:209], v[12:15]
	v_mfma_f32_16x16x32_bf16 v[8:11], v[174:177], v[206:209], v[8:11]
	v_mfma_f32_16x16x32_bf16 v[60:63], v[170:173], v[186:189], v[60:63]
	v_mfma_f32_16x16x32_bf16 v[56:59], v[178:181], v[186:189], v[56:59]
	v_mfma_f32_16x16x32_bf16 v[44:47], v[170:173], v[194:197], v[44:47]
	v_mfma_f32_16x16x32_bf16 v[40:43], v[178:181], v[194:197], v[40:43]
	v_mfma_f32_16x16x32_bf16 v[28:31], v[170:173], v[202:205], v[28:31]
	v_mfma_f32_16x16x32_bf16 v[24:27], v[178:181], v[202:205], v[24:27]
	v_mfma_f32_16x16x32_bf16 v[12:15], v[170:173], v[210:213], v[12:15]
	v_mfma_f32_16x16x32_bf16 v[8:11], v[178:181], v[210:213], v[8:11]
	s_setprio 0
	s_barrier
	s_add_u32 s16, s20, 0x44000
	s_addc_u32 s17, s21, 0
	s_mov_b32 m0, s42
	v_lshl_add_u64 v[140:141], s[16:17], 0, v[130:131]
	global_load_lds_dwordx4 v[140:141], off
	v_lshl_add_u64 v[140:141], s[16:17], 0, v[128:129]
	s_mov_b32 m0, s43
	s_nop 0
	global_load_lds_dwordx4 v[140:141], off
	s_waitcnt vmcnt(6)
	s_barrier
	s_setprio 1
	s_setprio 0
	s_barrier
	ds_read_b128 v[140:143], v155
	ds_read_b128 v[170:173], v156
	ds_read_b128 v[174:177], v157
	ds_read_b128 v[178:181], v165
	s_add_u32 s16, s28, 0x44000
	s_addc_u32 s17, s29, 0
	s_mov_b32 m0, s44
	v_lshl_add_u64 v[214:215], s[16:17], 0, v[130:131]
	ds_read_b128 v[182:185], v145 offset:32768
	ds_read_b128 v[186:189], v145 offset:33792
	ds_read_b128 v[190:193], v145 offset:34816
	ds_read_b128 v[194:197], v145 offset:35840
	ds_read_b128 v[198:201], v145 offset:36864
	ds_read_b128 v[202:205], v145 offset:37888
	ds_read_b128 v[206:209], v145 offset:38912
	ds_read_b128 v[210:213], v145 offset:39936
	global_load_lds_dwordx4 v[214:215], off
	v_lshl_add_u64 v[214:215], s[16:17], 0, v[128:129]
	s_mov_b32 m0, s45
	s_nop 0
	global_load_lds_dwordx4 v[214:215], off
	s_waitcnt lgkmcnt(8)
	s_barrier
; DI float ex2(float x) { return __builtin_amdgcn_exp2f(x); }
; #define PG8_STAGE(bufoff, gbase, voff) do { _Pragma("unroll") for (int _i = 0; _i < 2; ++_i) \
;         __builtin_amdgcn_global_load_lds((const unsigned*)((const char*)(gbase) + (voff)[_i]), (PG8_LAS unsigned*)(lds + (bufoff) + ldsw + _i * 8192), 16, 0, 0); } while (0)
; #define PG8_LDA(dst, b, h) do { _Pragma("unroll") for (int m = 0; m < 4; ++m) _Pragma("unroll") for (int k = 0; k < 2; ++k) dst[m][k] = *(const PG8_LAS bf16x8*)(lds + PG8_SA(b, h) + aoff + m * 2048 + k * 1024); } while (0)
; #define PG8_LDB(dst, b, h) do { _Pragma("unroll") for (int n = 0; n < 2; ++n) _Pragma("unroll") for (int k = 0; k < 2; ++k) dst[n][k] = *(const PG8_LAS bf16x8*)(lds + PG8_SB(b, h) + boff + n * 2048 + k * 1024); } while (0)
; #define PG8_WAIT_V(n) asm volatile("s_waitcnt vmcnt(" #n ")" ::: "memory")
;     DI void operator()(const f32x4 (&acc)[2][2][4][2], const Unit& u, int wr, int wc, int fr, int fq) const {
;         const int row0 = u.pm * BM + wr * 64 + fr, hcol0 = ((u.pn * BM + wc * 32) >> 1) + 4 * fq;
; #pragma unroll
;         for (int ai = 0; ai < 2; ++ai)
; #pragma unroll
;             for (int m = 0; m < 4; ++m) { u16* rowp = O + (size_t)(row0 + ai * HALF + m * 16) * ldc + hcol0;
; #pragma unroll
;                 for (int bj = 0; bj < 2; ++bj) { const f32x4 g = acc[ai][bj][m][0], up = acc[ai][bj][m][1]; float r[4];
; #pragma unroll
;                     for (int j = 0; j < 4; ++j) r[j] = g[j] * up[j] * __builtin_amdgcn_rcpf(1.f + ex2(-LOG2E * g[j]));
;                     uint2 w = {pack2(r[0], r[1]), pack2(r[2], r[3])}; *(uint2*)(rowp + bj * (HALF / 2)) = w; } }
; template <class Epi, class Sched, bool STAMP = false>
; __device__ __forceinline__ void gemm_phase(PG8_LAS unsigned char* lds, const Gemm g, const Sched& S, const Epi& E, unsigned long long* stamps) {
;     ...
;             PG8_WAIT_L(8); PG8_BAR; PG8_WAIT_L(0); PG8_MMA(0, 0, At, B0); PG8_BAR; PG8_SCHED;
;             PG8_LDB(B1, 1, 1); PG8_STAGE(PG8_SB(1, 0), b3, voffB);
;             PG8_BAR; PG8_WAIT_L(0); PG8_MMA(0, 1, At, B1); PG8_BAR;
;             PG8_LDA(At, 1, 1); PG8_STAGE(PG8_SA(1, 0), a3, voffA);
;             PG8_BAR; PG8_WAIT_L(0); PG8_MMA(1, 0, At, B0); PG8_BAR; PG8_SCHED;
;             PG8_STAGE(PG8_SB(1, 1), b3 + hstep, voffB);
;             PG8_WAIT_V(6); PG8_BAR; PG8_MMA(1, 1, At, B1); PG8_BAR;
	s_waitcnt lgkmcnt(0)
	s_setprio 1
	s_waitcnt lgkmcnt(0)
	v_mfma_f32_16x16x32_bf16 v[124:127], v[140:143], v[182:185], v[124:127]
	v_mfma_f32_16x16x32_bf16 v[120:123], v[174:177], v[182:185], v[120:123]
	v_mfma_f32_16x16x32_bf16 v[108:111], v[140:143], v[190:193], v[108:111]
	v_mfma_f32_16x16x32_bf16 v[104:107], v[174:177], v[190:193], v[104:107]
	v_mfma_f32_16x16x32_bf16 v[92:95], v[140:143], v[198:201], v[92:95]
	v_mfma_f32_16x16x32_bf16 v[88:91], v[174:177], v[198:201], v[88:91]
	v_mfma_f32_16x16x32_bf16 v[76:79], v[140:143], v[206:209], v[76:79]
	v_mfma_f32_16x16x32_bf16 v[72:75], v[174:177], v[206:209], v[72:75]
	v_mfma_f32_16x16x32_bf16 v[124:127], v[170:173], v[186:189], v[124:127]
	v_mfma_f32_16x16x32_bf16 v[120:123], v[178:181], v[186:189], v[120:123]
	v_mfma_f32_16x16x32_bf16 v[108:111], v[170:173], v[194:197], v[108:111]
	v_mfma_f32_16x16x32_bf16 v[104:107], v[178:181], v[194:197], v[104:107]
	v_mfma_f32_16x16x32_bf16 v[92:95], v[170:173], v[202:205], v[92:95]
	v_mfma_f32_16x16x32_bf16 v[88:91], v[178:181], v[202:205], v[88:91]
	v_mfma_f32_16x16x32_bf16 v[76:79], v[170:173], v[210:213], v[76:79]
	v_mfma_f32_16x16x32_bf16 v[72:75], v[178:181], v[210:213], v[72:75]
	s_setprio 0
	s_barrier
	s_mov_b32 m0, s48
	v_lshl_add_u64 v[230:231], v[230:231], 0, s[6:7]
	global_load_lds_dwordx4 v[230:231], off
	v_lshl_add_u64 v[230:231], v[232:233], 0, s[6:7]
	s_mov_b32 m0, s49
	s_nop 0
	global_load_lds_dwordx4 v[230:231], off
	s_barrier
	s_waitcnt lgkmcnt(0)
	s_setprio 1
	s_waitcnt lgkmcnt(0)
	s_setprio 0
	s_mov_b32 m0, s50
	v_lshl_add_u64 v[230:231], v[234:235], 0, s[6:7]
	s_barrier
	ds_read_b128 v[182:185], v145 offset:49152
	ds_read_b128 v[186:189], v145 offset:50176
	ds_read_b128 v[190:193], v145 offset:51200
	ds_read_b128 v[194:197], v145 offset:52224
	ds_read_b128 v[198:201], v145 offset:53248
	ds_read_b128 v[202:205], v145 offset:54272
	ds_read_b128 v[206:209], v145 offset:55296
	ds_read_b128 v[210:213], v145 offset:56320
	global_load_lds_dwordx4 v[230:231], off
	v_lshl_add_u64 v[230:231], v[236:237], 0, s[6:7]
	s_mov_b32 m0, s51
	s_nop 0
	global_load_lds_dwordx4 v[230:231], off
	s_barrier
	s_waitcnt lgkmcnt(0)
	s_setprio 1
	s_waitcnt lgkmcnt(0)
	v_mfma_f32_16x16x32_bf16 v[60:63], v[140:143], v[182:185], v[60:63]
	v_mfma_f32_16x16x32_bf16 v[56:59], v[174:177], v[182:185], v[56:59]
	v_mfma_f32_16x16x32_bf16 v[44:47], v[140:143], v[190:193], v[44:47]
	v_mfma_f32_16x16x32_bf16 v[40:43], v[174:177], v[190:193], v[40:43]
	v_mfma_f32_16x16x32_bf16 v[28:31], v[140:143], v[198:201], v[28:31]
	v_mfma_f32_16x16x32_bf16 v[24:27], v[174:177], v[198:201], v[24:27]
	v_mfma_f32_16x16x32_bf16 v[12:15], v[140:143], v[206:209], v[12:15]
	v_mfma_f32_16x16x32_bf16 v[8:11], v[174:177], v[206:209], v[8:11]
	v_mfma_f32_16x16x32_bf16 v[60:63], v[170:173], v[186:189], v[60:63]
	v_mfma_f32_16x16x32_bf16 v[56:59], v[178:181], v[186:189], v[56:59]
	v_mfma_f32_16x16x32_bf16 v[44:47], v[170:173], v[194:197], v[44:47]
	v_mfma_f32_16x16x32_bf16 v[40:43], v[178:181], v[194:197], v[40:43]
	v_mfma_f32_16x16x32_bf16 v[28:31], v[170:173], v[202:205], v[28:31]
	v_mfma_f32_16x16x32_bf16 v[24:27], v[178:181], v[202:205], v[24:27]
	v_mfma_f32_16x16x32_bf16 v[12:15], v[170:173], v[210:213], v[12:15]
	v_mfma_f32_16x16x32_bf16 v[8:11], v[178:181], v[210:213], v[8:11]
	s_setprio 0
	s_barrier
	s_add_u32 s16, s20, 0x44080
	s_addc_u32 s17, s21, 0
	s_mov_b32 m0, s52
	v_lshl_add_u64 v[140:141], s[16:17], 0, v[130:131]
	global_load_lds_dwordx4 v[140:141], off
	v_lshl_add_u64 v[140:141], s[16:17], 0, v[128:129]
	s_mov_b32 m0, s53
	s_nop 0
	global_load_lds_dwordx4 v[140:141], off
	s_waitcnt vmcnt(6)
	s_barrier
	s_setprio 1
	s_setprio 0
	s_add_i32 s10, s10, 2
	s_add_u32 s62, s62, 0x100
	s_addc_u32 s63, s63, 0
	s_cmp_gt_u32 s10, 13
	s_mov_b64 s[16:17], s[18:19]
	s_barrier
	s_cbranch_scc0 .Lgu4_half_loop
	v_mul_f32_e32 v171, 0xbfb8aa3b, v124
	v_exp_f32_e32 v171, v171
	v_mul_f32_e32 v174, 0xbfb8aa3b, v125
	v_exp_f32_e32 v175, v174
	s_lshl_b32 s10, s61, 8
	v_add_f32_e32 v171, 1.0, v171
	v_rcp_f32_e32 v174, v171
	v_add_f32_e32 v171, 1.0, v175
	v_mul_f32_e32 v175, 0xbfb8aa3b, v126
	v_exp_f32_e32 v176, v175
	v_mul_f32_e32 v175, 0xbfb8aa3b, v127
	v_exp_f32_e32 v177, v175
	v_rcp_f32_e32 v175, v171
	v_add_f32_e32 v171, 1.0, v176
	v_rcp_f32_e32 v176, v171
	v_add_f32_e32 v171, 1.0, v177
	v_rcp_f32_e32 v177, v171
	v_pk_mul_f32 v[122:123], v[126:127], v[122:123]
	v_pk_mul_f32 v[120:121], v[124:125], v[120:121]
	s_or_b32 s10, s10, s47
	s_or_b32 s10, s10, s98
	v_pk_mul_f32 v[120:121], v[120:121], v[174:175]
	v_pk_mul_f32 v[122:123], v[122:123], v[176:177]
	s_ashr_i32 s10, s10, 1
	v_cvt_pk_bf16_f32 v120, v120, v121
	v_cvt_pk_bf16_f32 v121, v122, v123
	v_or_b32_e32 v140, s10, v146
	v_lshl_add_u32 v170, s60, 8, v144
	v_ashrrev_i32_e32 v141, 31, v140
	v_mov_b64_e32 v[142:143], s[12:13]
	v_mad_i64_i32 v[172:173], s[16:17], v170, s57, v[142:143]
	v_lshlrev_b64 v[140:141], 1, v[140:141]
	v_lshl_add_u64 v[172:173], v[172:173], 0, v[140:141]
	global_store_dwordx2 v[172:173], v[120:121], off
	v_mul_f32_e32 v116, 0xbfb8aa3b, v110
	v_mul_f32_e32 v114, 0xbfb8aa3b, v108
	v_mul_f32_e32 v115, 0xbfb8aa3b, v109
	v_mul_f32_e32 v117, 0xbfb8aa3b, v111
	v_exp_f32_e32 v114, v114
	v_exp_f32_e32 v115, v115
	v_exp_f32_e32 v116, v116
	v_exp_f32_e32 v117, v117
	v_add_f32_e32 v114, 1.0, v114
	v_add_f32_e32 v115, 1.0, v115
	v_add_f32_e32 v116, 1.0, v116
	v_add_f32_e32 v117, 1.0, v117
	v_rcp_f32_e32 v114, v114
	v_rcp_f32_e32 v115, v115
	v_rcp_f32_e32 v116, v116
	v_rcp_f32_e32 v117, v117
	v_pk_mul_f32 v[106:107], v[110:111], v[106:107]
	v_pk_mul_f32 v[104:105], v[108:109], v[104:105]
	v_pk_mul_f32 v[104:105], v[104:105], v[114:115]
; DI float ex2(float x) { return __builtin_amdgcn_exp2f(x); }
;     DI void operator()(const f32x4 (&acc)[2][2][4][2], const Unit& u, int wr, int wc, int fr, int fq) const {
;         const int row0 = u.pm * BM + wr * 64 + fr, hcol0 = ((u.pn * BM + wc * 32) >> 1) + 4 * fq;
; #pragma unroll
;         for (int ai = 0; ai < 2; ++ai)
; #pragma unroll
;             for (int m = 0; m < 4; ++m) { u16* rowp = O + (size_t)(row0 + ai * HALF + m * 16) * ldc + hcol0;
; #pragma unroll
;                 for (int bj = 0; bj < 2; ++bj) { const f32x4 g = acc[ai][bj][m][0], up = acc[ai][bj][m][1]; float r[4];
; #pragma unroll
;                     for (int j = 0; j < 4; ++j) r[j] = g[j] * up[j] * __builtin_amdgcn_rcpf(1.f + ex2(-LOG2E * g[j]));
;                     uint2 w = {pack2(r[0], r[1]), pack2(r[2], r[3])}; *(uint2*)(rowp + bj * (HALF / 2)) = w; } }
	v_pk_mul_f32 v[106:107], v[106:107], v[116:117]
	v_cvt_pk_bf16_f32 v104, v104, v105
	v_cvt_pk_bf16_f32 v105, v106, v107
	v_or_b32_e32 v112, 16, v170
	v_mad_i64_i32 v[112:113], s[16:17], v112, s57, v[142:143]
	v_lshl_add_u64 v[112:113], v[112:113], 0, v[140:141]
	global_store_dwordx2 v[112:113], v[104:105], off
	v_mul_f32_e32 v100, 0xbfb8aa3b, v94
	v_mul_f32_e32 v98, 0xbfb8aa3b, v92
	v_mul_f32_e32 v99, 0xbfb8aa3b, v93
	v_mul_f32_e32 v101, 0xbfb8aa3b, v95
	v_exp_f32_e32 v98, v98
	v_exp_f32_e32 v99, v99
	v_exp_f32_e32 v100, v100
	v_exp_f32_e32 v101, v101
	v_add_f32_e32 v98, 1.0, v98
	v_add_f32_e32 v99, 1.0, v99
	v_add_f32_e32 v100, 1.0, v100
	v_add_f32_e32 v101, 1.0, v101
	v_rcp_f32_e32 v98, v98
	v_rcp_f32_e32 v99, v99
	v_rcp_f32_e32 v100, v100
	v_rcp_f32_e32 v101, v101
	v_pk_mul_f32 v[90:91], v[94:95], v[90:91]
	v_pk_mul_f32 v[88:89], v[92:93], v[88:89]
	v_pk_mul_f32 v[88:89], v[88:89], v[98:99]
	v_pk_mul_f32 v[90:91], v[90:91], v[100:101]
	v_cvt_pk_bf16_f32 v88, v88, v89
	v_cvt_pk_bf16_f32 v89, v90, v91
	v_or_b32_e32 v96, 32, v170
	v_mad_i64_i32 v[96:97], s[16:17], v96, s57, v[142:143]
	v_lshl_add_u64 v[96:97], v[96:97], 0, v[140:141]
	global_store_dwordx2 v[96:97], v[88:89], off
	v_mul_f32_e32 v84, 0xbfb8aa3b, v78
	v_mul_f32_e32 v82, 0xbfb8aa3b, v76
	v_mul_f32_e32 v83, 0xbfb8aa3b, v77
	v_mul_f32_e32 v85, 0xbfb8aa3b, v79
	v_exp_f32_e32 v82, v82
	v_exp_f32_e32 v83, v83
	v_exp_f32_e32 v84, v84
	v_exp_f32_e32 v85, v85
	v_add_f32_e32 v82, 1.0, v82
	v_add_f32_e32 v83, 1.0, v83
	v_add_f32_e32 v84, 1.0, v84
	v_add_f32_e32 v85, 1.0, v85
	v_rcp_f32_e32 v82, v82
	v_rcp_f32_e32 v83, v83
	v_rcp_f32_e32 v84, v84
	v_rcp_f32_e32 v85, v85
	v_pk_mul_f32 v[74:75], v[78:79], v[74:75]
	v_pk_mul_f32 v[72:73], v[76:77], v[72:73]
	v_pk_mul_f32 v[72:73], v[72:73], v[82:83]
	v_pk_mul_f32 v[74:75], v[74:75], v[84:85]
	v_cvt_pk_bf16_f32 v72, v72, v73
	v_cvt_pk_bf16_f32 v73, v74, v75
	v_or_b32_e32 v80, 48, v170
	v_mad_i64_i32 v[80:81], s[16:17], v80, s57, v[142:143]
	v_lshl_add_u64 v[80:81], v[80:81], 0, v[140:141]
	global_store_dwordx2 v[80:81], v[72:73], off
	v_mul_f32_e32 v68, 0xbfb8aa3b, v62
	v_mul_f32_e32 v66, 0xbfb8aa3b, v60
	v_mul_f32_e32 v67, 0xbfb8aa3b, v61
	v_mul_f32_e32 v69, 0xbfb8aa3b, v63
	v_exp_f32_e32 v66, v66
	v_exp_f32_e32 v67, v67
	v_exp_f32_e32 v68, v68
	v_exp_f32_e32 v69, v69
	v_add_f32_e32 v66, 1.0, v66
	v_add_f32_e32 v67, 1.0, v67
	v_add_f32_e32 v68, 1.0, v68
	v_add_f32_e32 v69, 1.0, v69
	v_rcp_f32_e32 v66, v66
	v_rcp_f32_e32 v67, v67
	v_rcp_f32_e32 v68, v68
	v_rcp_f32_e32 v69, v69
	v_pk_mul_f32 v[58:59], v[62:63], v[58:59]
	v_pk_mul_f32 v[56:57], v[60:61], v[56:57]
	v_pk_mul_f32 v[56:57], v[56:57], v[66:67]
	v_pk_mul_f32 v[58:59], v[58:59], v[68:69]
	v_cvt_pk_bf16_f32 v56, v56, v57
	v_cvt_pk_bf16_f32 v57, v58, v59
	v_add_u32_e32 v64, 0x80, v170
	v_mad_i64_i32 v[64:65], s[16:17], v64, s57, v[142:143]
	v_lshl_add_u64 v[64:65], v[64:65], 0, v[140:141]
	global_store_dwordx2 v[64:65], v[56:57], off
	v_mul_f32_e32 v52, 0xbfb8aa3b, v46
	v_mul_f32_e32 v50, 0xbfb8aa3b, v44
	v_mul_f32_e32 v51, 0xbfb8aa3b, v45
	v_mul_f32_e32 v53, 0xbfb8aa3b, v47
	v_exp_f32_e32 v50, v50
	v_exp_f32_e32 v51, v51
	v_exp_f32_e32 v52, v52
	v_exp_f32_e32 v53, v53
	v_add_f32_e32 v50, 1.0, v50
	v_add_f32_e32 v51, 1.0, v51
	v_add_f32_e32 v52, 1.0, v52
	v_add_f32_e32 v53, 1.0, v53
	v_rcp_f32_e32 v50, v50
	v_rcp_f32_e32 v51, v51
	v_rcp_f32_e32 v52, v52
	v_rcp_f32_e32 v53, v53
	v_pk_mul_f32 v[42:43], v[46:47], v[42:43]
	v_pk_mul_f32 v[40:41], v[44:45], v[40:41]
	v_pk_mul_f32 v[40:41], v[40:41], v[50:51]
	v_pk_mul_f32 v[42:43], v[42:43], v[52:53]
	v_cvt_pk_bf16_f32 v40, v40, v41
	v_cvt_pk_bf16_f32 v41, v42, v43
	v_add_u32_e32 v48, 0x90, v170
	v_mad_i64_i32 v[48:49], s[16:17], v48, s57, v[142:143]
	v_lshl_add_u64 v[48:49], v[48:49], 0, v[140:141]
	global_store_dwordx2 v[48:49], v[40:41], off
	v_mul_f32_e32 v36, 0xbfb8aa3b, v30
	v_mul_f32_e32 v34, 0xbfb8aa3b, v28
	v_mul_f32_e32 v35, 0xbfb8aa3b, v29
	v_mul_f32_e32 v37, 0xbfb8aa3b, v31
	v_exp_f32_e32 v34, v34
	v_exp_f32_e32 v35, v35
	v_exp_f32_e32 v36, v36
	v_exp_f32_e32 v37, v37
	v_add_f32_e32 v34, 1.0, v34
	v_add_f32_e32 v35, 1.0, v35
	v_add_f32_e32 v36, 1.0, v36
	v_add_f32_e32 v37, 1.0, v37
	v_rcp_f32_e32 v34, v34
	v_rcp_f32_e32 v35, v35
	v_rcp_f32_e32 v36, v36
	v_rcp_f32_e32 v37, v37
	v_pk_mul_f32 v[26:27], v[30:31], v[26:27]
	v_pk_mul_f32 v[24:25], v[28:29], v[24:25]
	v_pk_mul_f32 v[24:25], v[24:25], v[34:35]
	v_pk_mul_f32 v[26:27], v[26:27], v[36:37]
	v_cvt_pk_bf16_f32 v24, v24, v25
	v_cvt_pk_bf16_f32 v25, v26, v27
	v_add_u32_e32 v32, 0xa0, v170
	v_mad_i64_i32 v[32:33], s[16:17], v32, s57, v[142:143]
	v_lshl_add_u64 v[32:33], v[32:33], 0, v[140:141]
	global_store_dwordx2 v[32:33], v[24:25], off
	v_mul_f32_e32 v20, 0xbfb8aa3b, v14
	v_mul_f32_e32 v18, 0xbfb8aa3b, v12
	v_mul_f32_e32 v19, 0xbfb8aa3b, v13
	v_mul_f32_e32 v21, 0xbfb8aa3b, v15
	v_exp_f32_e32 v18, v18
	v_exp_f32_e32 v19, v19
	v_exp_f32_e32 v20, v20
	v_exp_f32_e32 v21, v21
	v_add_f32_e32 v18, 1.0, v18
	v_add_f32_e32 v19, 1.0, v19
	v_add_f32_e32 v20, 1.0, v20
	v_add_f32_e32 v21, 1.0, v21
	v_rcp_f32_e32 v18, v18
	v_rcp_f32_e32 v19, v19
	v_rcp_f32_e32 v20, v20
	v_rcp_f32_e32 v21, v21
	v_pk_mul_f32 v[10:11], v[14:15], v[10:11]
	v_pk_mul_f32 v[8:9], v[12:13], v[8:9]
	v_pk_mul_f32 v[8:9], v[8:9], v[18:19]
	v_pk_mul_f32 v[10:11], v[10:11], v[20:21]
	v_cvt_pk_bf16_f32 v8, v8, v9
	v_cvt_pk_bf16_f32 v9, v10, v11
	v_add_u32_e32 v16, 0xb0, v170
	v_mad_i64_i32 v[16:17], s[16:17], v16, s57, v[142:143]
	v_lshl_add_u64 v[16:17], v[16:17], 0, v[140:141]
	global_store_dwordx2 v[16:17], v[8:9], off
	s_and_b64 vcc, exec, s[2:3]
	s_mov_b32 s61, s58
	s_mov_b32 s60, s59
	s_mov_b64 s[18:19], s[0:1]
	s_mov_b64 s[16:17], s[4:5]
